# 4-buffer selected loop, de-serialised q-fragment loads in tile prologue and window preamble, reversed rank order in time quarters 1-3 for load balance
# speedup vs baseline: 1.0489x; 1.0127x over previous
; __device__ __forceinline__ void attention_phase(const Ctx& C) {
;     ...
;     for (int k0 = 0; k0 < nper; ++k0) {
;         const int kk = flip ? (k0 + rot) % nper : k0; const int i = rank + kk * nrank; if (i >= nitem) continue;
;         int nsa_n, mem_e;
;         if (xmode) { nsa_n = (i < 1024) ? (x >> 1) * 2048 + 2 * i + (x & 1) : -1; mem_e = x * 512 + (i - 1024); }
;         else { if (i < 8192) { const int k = i >> 11, w = i & 2047; nsa_n = k * 2048 + ((k & 1) ? 2047 - w : w); } else nsa_n = -1; mem_e = i - 8192; }
.LBB0_653:
	s_mul_i32 s3, s0, s26
	s_sub_i32 s2, s26, s9
	s_add_i32 s2, s2, -1
	s_sub_i32 s1, s0, 1
	s_cmp_lt_u32 s1, 3
	s_cselect_b32 s2, s2, s9
	s_add_i32 s3, s3, s2
	s_cmp_ge_i32 s3, s47
	s_cbranch_scc1 .LBB0_650
	s_mov_b64 s[0:1], -1
	s_and_b64 vcc, exec, s[50:51]
	s_cbranch_vccz .LBB0_661
	s_and_b32 s0, s3, 0x7ff
	s_and_b32 s1, s3, 0xfffff800
	s_and_b32 s2, s3, 0x800
	s_xor_b32 s4, s0, 0x7ff
	s_cmp_eq_u32 s2, 0
	s_cselect_b32 s0, s0, s4
	s_or_b32 s0, s0, s1
	s_cmpk_lt_i32 s3, 0x2000
	s_cselect_b32 s2, s0, -1
	s_add_i32 s5, s3, 0xffffe000
	s_cbranch_execz .LBB0_662

; __device__ __forceinline__ float bf1(bf16_t u) { return __uint_as_float(((unsigned)u) << 16); }
; __device__ __forceinline__ float sigm(float x) { return rcpf_(1.f + ex2(-1.44269504f * x)); }
; __device__ __forceinline__ bf16x8 scale_q(u32x4 v, float s) { u32x4 w; w.x = cvt_pk_bf16(bf_lo(v.x) * s, bf_hi(v.x) * s); w.y = cvt_pk_bf16(bf_lo(v.y) * s, bf_hi(v.y) * s); w.z = cvt_pk_bf16(bf_lo(v.z) * s, bf_hi(v.z) * s); w.w = cvt_pk_bf16(bf_lo(v.w) * s, bf_hi(v.w) * s); return __builtin_bit_cast(bf16x8, w); }
; #define CMP_LDK(KF, KT) do { const int kn_ = ((KT) < ntile) ? (KT) : ntile - 1; _Pragma("unroll") for (int s = 0; s < 4; ++s) KF[s] = kb[kn_ * 256 + s * 64]; } while (0)
; __device__ __forceinline__ void nsa_tile(const Ctx& C, int b, int g, int t0) {
;     ...
;     bf16x8 qf[4];
;     {
;         const bf16_t* qp = P + tok * PP + PC_Q + head * 64;
; #pragma unroll
;         for (int s = 0; s < 4; ++s) qf[s] = scale_q(*(const u32x4*)(qp + 16 * s + 8 * hi), QS);
;     }
;     const bf16_t* gp = P + tok * PP + PC_NG + head * 3;
;     const float gc = sigm(bf1(gp[0])), gs = sigm(bf1(gp[1])), gw = sigm(bf1(gp[2]));
;     const int cur = t0 >> 6;
;     {
;         const int nvq = (t >= 31) ? ((t - 31) >> 4) + 1 : 0;
;         const int nvmin = (t0 >= 31) ? ((t0 - 31) >> 4) + 1 : 0;
;         const int tl = t0 + 7, nvmax = (tl >= 31) ? ((tl - 31) >> 4) + 1 : 0, ntile = (nvmax + 31) >> 5;
;         const bf16x8* kb = (const bf16x8*)(C.ws + WS_KCMP) + (size_t)bg * 32 * 4 * 64 + lane;
;         const bf16x8* vb = (const bf16x8*)(C.ws + WS_VCMP) + (size_t)bg * 64 * 2 * 64 + lane;
;         float m1 = -1e30f, l1 = 0.f;
;     ...
;         if (ntile > 0) {
;             bf16x8 kA[4], kB[4], kC[4], kD[4];
;     ...
;             CMP_LDK(kA, 0); CMP_LDK(kB, 1); CMP_LDK(kC, 2);
; #pragma unroll 1
;             for (int kt = 0; kt < ntile; kt += 4) {
;                 CMP_LDK(kD, kt + 3); __builtin_amdgcn_sched_barrier(0); CMP_P1(kA, kt);     if (kt + 1 >= ntile) break;
;                 CMP_LDK(kA, kt + 4); __builtin_amdgcn_sched_barrier(0); CMP_P1(kB, kt + 1); if (kt + 2 >= ntile) break;
;                 CMP_LDK(kB, kt + 5); __builtin_amdgcn_sched_barrier(0); CMP_P1(kC, kt + 2); if (kt + 3 >= ntile) break;
;                 CMP_LDK(kC, kt + 6); __builtin_amdgcn_sched_barrier(0); CMP_P1(kD, kt + 3);
;             }
;         }
.LBB0_665:
	s_lshl_b32 s1, s2, 3
	v_mov_b32_e32 v224, v252
	s_lshr_b32 s3, s2, 12
	s_and_b32 s97, s1, 0x3ff8
	s_bfe_u32 s0, s2, 0x1000b
	s_waitcnt vmcnt(13)
	v_bfe_u32 v82, v224, 2, 3
	v_and_b32_e32 v83, 3, v224
	v_or_b32_e32 v242, s97, v82
	s_lshl_b32 s76, s3, 14
	v_ashrrev_i32_e32 v244, 5, v224
	v_lshl_or_b32 v84, s0, 2, v83
	v_or_b32_e32 v0, s76, v242
	v_mov_b64_e32 v[2:3], s[86:87]
	s_lshl_b32 s1, s3, 1
	v_mad_u64_u32 v[2:3], s[2:3], v0, s67, v[2:3]
	v_lshlrev_b32_e32 v4, 7, v84
	v_mov_b32_e32 v5, v1
	v_lshlrev_b32_e32 v218, 3, v244
	v_lshl_add_u64 v[222:223], v[2:3], 0, v[4:5]
	v_ashrrev_i32_e32 v219, 31, v218
	v_lshl_add_u64 v[220:221], v[218:219], 1, v[222:223]
	global_load_dwordx4 v[4:7], v[220:221], off offset:3072
	global_load_dwordx4 v[114:117], v[220:221], off offset:3104
	global_load_dwordx4 v[118:121], v[220:221], off offset:3136
	global_load_dwordx4 v[122:125], v[220:221], off offset:3168
	v_mov_b32_e32 v179, v1
	s_or_b32 s30, s1, s0
	s_mov_b64 s[0:1], 0x1a00
	s_mov_b32 s31, s7
	v_ashrrev_i32_e32 v225, 31, v224
	s_waitcnt vmcnt(3)
	v_lshlrev_b32_e32 v8, 16, v4
	v_and_b32_e32 v9, 0xffff0000, v4
	v_lshlrev_b32_e32 v4, 16, v5
	v_and_b32_e32 v5, 0xffff0000, v5
	v_pk_mul_f32 v[4:5], v[4:5], s[38:39] op_sel_hi:[1,0]
	v_pk_mul_f32 v[8:9], v[8:9], s[38:39] op_sel_hi:[1,0]
	v_cvt_pk_bf16_f32 v99, v4, v5
	v_lshlrev_b32_e32 v4, 16, v6
	v_and_b32_e32 v5, 0xffff0000, v6
	v_pk_mul_f32 v[4:5], v[4:5], s[38:39] op_sel_hi:[1,0]
	v_cvt_pk_bf16_f32 v98, v8, v9
	v_cvt_pk_bf16_f32 v100, v4, v5
	v_lshlrev_b32_e32 v4, 16, v7
	v_and_b32_e32 v5, 0xffff0000, v7
	v_pk_mul_f32 v[4:5], v[4:5], s[38:39] op_sel_hi:[1,0]
	s_nop 0
	v_cvt_pk_bf16_f32 v101, v4, v5
	s_waitcnt vmcnt(2)
	v_mov_b32_e32 v4, v114
	v_mov_b32_e32 v5, v115
	v_mov_b32_e32 v6, v116
	v_mov_b32_e32 v7, v117
	v_lshlrev_b32_e32 v8, 16, v4
	v_and_b32_e32 v9, 0xffff0000, v4
	v_lshlrev_b32_e32 v4, 16, v5
	v_and_b32_e32 v5, 0xffff0000, v5
	v_pk_mul_f32 v[4:5], v[4:5], s[38:39] op_sel_hi:[1,0]
	v_pk_mul_f32 v[8:9], v[8:9], s[38:39] op_sel_hi:[1,0]
	v_cvt_pk_bf16_f32 v103, v4, v5
	v_lshlrev_b32_e32 v4, 16, v6
	v_and_b32_e32 v5, 0xffff0000, v6
	v_pk_mul_f32 v[4:5], v[4:5], s[38:39] op_sel_hi:[1,0]
	v_cvt_pk_bf16_f32 v102, v8, v9
	v_cvt_pk_bf16_f32 v104, v4, v5
	v_lshlrev_b32_e32 v4, 16, v7
	v_and_b32_e32 v5, 0xffff0000, v7
	v_pk_mul_f32 v[4:5], v[4:5], s[38:39] op_sel_hi:[1,0]
	s_nop 0
	v_cvt_pk_bf16_f32 v105, v4, v5
	s_waitcnt vmcnt(1)
	v_mov_b32_e32 v4, v118
	v_mov_b32_e32 v5, v119
	v_mov_b32_e32 v6, v120
	v_mov_b32_e32 v7, v121
	v_lshlrev_b32_e32 v8, 16, v4
	v_and_b32_e32 v9, 0xffff0000, v4
	v_lshlrev_b32_e32 v4, 16, v5
	v_and_b32_e32 v5, 0xffff0000, v5
	v_pk_mul_f32 v[4:5], v[4:5], s[38:39] op_sel_hi:[1,0]
	v_pk_mul_f32 v[8:9], v[8:9], s[38:39] op_sel_hi:[1,0]
	v_cvt_pk_bf16_f32 v107, v4, v5
	v_lshlrev_b32_e32 v4, 16, v6
	v_and_b32_e32 v5, 0xffff0000, v6
	v_pk_mul_f32 v[4:5], v[4:5], s[38:39] op_sel_hi:[1,0]
	v_cvt_pk_bf16_f32 v106, v8, v9
	v_cvt_pk_bf16_f32 v108, v4, v5
	v_lshlrev_b32_e32 v4, 16, v7
	v_and_b32_e32 v5, 0xffff0000, v7
	v_pk_mul_f32 v[4:5], v[4:5], s[38:39] op_sel_hi:[1,0]
	s_nop 0
	v_cvt_pk_bf16_f32 v109, v4, v5
	s_waitcnt vmcnt(0)
	v_mov_b32_e32 v4, v122
	v_mov_b32_e32 v5, v123
	v_mov_b32_e32 v6, v124
	v_mov_b32_e32 v7, v125
	v_lshlrev_b32_e32 v8, 16, v4
	v_and_b32_e32 v9, 0xffff0000, v4
	v_lshlrev_b32_e32 v4, 16, v5
	v_and_b32_e32 v5, 0xffff0000, v5
	v_pk_mul_f32 v[4:5], v[4:5], s[38:39] op_sel_hi:[1,0]
	v_pk_mul_f32 v[8:9], v[8:9], s[38:39] op_sel_hi:[1,0]
	v_cvt_pk_bf16_f32 v111, v4, v5
	v_lshlrev_b32_e32 v4, 16, v6
	v_and_b32_e32 v5, 0xffff0000, v6
	v_pk_mul_f32 v[4:5], v[4:5], s[38:39] op_sel_hi:[1,0]
	v_cvt_pk_bf16_f32 v110, v8, v9
	v_cvt_pk_bf16_f32 v112, v4, v5
	v_lshlrev_b32_e32 v4, 16, v7
	v_and_b32_e32 v5, 0xffff0000, v7
	v_pk_mul_f32 v[4:5], v[4:5], s[38:39] op_sel_hi:[1,0]
	s_nop 0
	v_cvt_pk_bf16_f32 v113, v4, v5
	v_mul_u32_u24_e32 v4, 3, v84
	v_lshlrev_b32_e32 v178, 1, v4
	v_lshl_add_u64 v[2:3], v[2:3], 0, v[178:179]
	v_lshl_add_u64 v[4:5], v[2:3], 0, s[0:1]
	s_movk_i32 s0, 0x1000
	v_add_co_u32_e32 v2, vcc, s0, v2
	s_sub_i32 s0, s97, 31
	s_nop 0
	v_addc_co_u32_e32 v3, vcc, 0, v3, vcc
	global_load_ushort v179, v[2:3], off offset:2560
	global_load_ushort v219, v[4:5], off offset:4
	s_lshr_b32 s0, s0, 4
	s_add_i32 s0, s0, 1
	s_cmp_gt_u32 s97, 30
	s_cselect_b32 s17, s0, 0
	s_sub_i32 s0, s97, 24
	s_ashr_i32 s0, s0, 4
	s_add_i32 s0, s0, 32
	s_lshr_b32 s0, s0, 5
	s_cmp_gt_u32 s97, 23
	s_cselect_b32 s16, s0, 0
	s_lshl_b64 s[22:23], s[30:31], 17
	v_subrev_u32_e32 v2, 31, v242
	s_add_u32 s0, s74, s22
	v_ashrrev_i32_e32 v2, 4, v2
	s_addc_u32 s1, s75, s23
	v_cmp_lt_u32_e32 vcc, 30, v242
	v_add_u32_e32 v2, 1, v2
	s_cmp_lg_u32 s16, 0
	v_cndmask_b32_e32 v85, 0, v2, vcc
	v_lshl_add_u64 v[180:181], v[224:225], 4, s[0:1]
	s_cselect_b64 s[0:1], -1, 0
	s_cmp_eq_u32 s16, 0
	s_cbranch_scc1 .LBB0_684
	s_cmp_eq_u32 s16, 1
	s_cselect_b32 s6, 0, 0x1000
	s_add_i32 s2, s16, -1
	s_lshl_b32 s3, s2, 8
	s_cmp_lt_u32 s16, 3
	v_lshl_add_u64 v[2:3], v[180:181], 0, s[6:7]
	s_cselect_b32 s6, s3, 0x200
	global_load_dwordx4 v[30:33], v[180:181], off
	global_load_dwordx4 v[26:29], v[180:181], off offset:1024
	global_load_dwordx4 v[22:25], v[180:181], off offset:2048
	global_load_dwordx4 v[18:21], v[180:181], off offset:3072
	global_load_dwordx4 v[46:49], v[2:3], off
	global_load_dwordx4 v[42:45], v[2:3], off offset:1024
	global_load_dwordx4 v[38:41], v[2:3], off offset:2048
	global_load_dwordx4 v[34:37], v[2:3], off offset:3072
	v_lshl_add_u64 v[2:3], s[6:7], 4, v[180:181]
	global_load_dwordx4 v[62:65], v[2:3], off
	global_load_dwordx4 v[58:61], v[2:3], off offset:1024
	global_load_dwordx4 v[54:57], v[2:3], off offset:2048
	global_load_dwordx4 v[50:53], v[2:3], off offset:3072
	s_sub_i32 s3, s17, 32
	v_subrev_u32_e32 v86, 33, v85
	v_mov_b32_e32 v89, 0
	v_mov_b32_e32 v87, 0xf149f2ca
	s_mov_b32 s6, 6
	s_mov_b32 s10, 64
	s_branch .LBB0_668

; __device__ __forceinline__ float bf_lo(unsigned u) { return __uint_as_float(u << 16); }
; __device__ __forceinline__ void nsa_tile(const Ctx& C, int b, int g, int t0) {
;     ...
;         const int q16 = lane & 15, fq = lane >> 4, qi4 = q16 >> 2, head4 = g * 4 + (q16 & 3);
;         const bf16x8* kb = (const bf16x8*)(C.ws + WS_KSLC) + (size_t)bg * 512 * 256 + lane;
;         const bf16x8* vb = (const bf16x8*)(C.ws + WS_VSLC) + (size_t)bg * 512 * 256 + lane;
;         int nblk = 0;
; #pragma unroll
;         for (int c = 0; c < 4; ++c) {
;             const unsigned long long mk = __ballot(bmv[c] != 0u);
;             const int pos = nblk + (int)__builtin_amdgcn_mbcnt_hi((unsigned)(mk >> 32), __builtin_amdgcn_mbcnt_lo((unsigned)mk, 0u));
;             if (bmv[c] != 0u) list[pos] = (unsigned)(lane + 64 * c) | (bmv[c] << 16);
;             nblk += __builtin_popcountll(mk);
;         }
;         LDS_WAIT();
;         const int tq = t0 + qi4;
;         bf16x8 q16f[2][2]; float gs4[2];
; #pragma unroll
;         for (int sub = 0; sub < 2; ++sub) {
;             const size_t tok4 = (size_t)b * S_ + tq + 4 * sub;
;             const bf16_t* qp = P + tok4 * PP + PC_Q + head4 * 64;
;             q16f[sub][1] = scale_q(*(const u32x4*)(qp + 32 + 8 * fq), QS);
;             const u32x4 mv4 = *(const u32x4*)(qp + 8 * fq), pv4 = *(const u32x4*)(qp + 8 * ((fq ^ 1) & 1));
;             const float* rt = (const float*)(C.ws + WS_ROPE) + tok4 * 16;
;             const f32x4 ca = *(const f32x4*)rt, cb2 = *(const f32x4*)(rt + 4), sa = *(const f32x4*)(rt + 8), sb = *(const f32x4*)(rt + 12);
;             const float cs[8] = {ca.x, ca.y, ca.z, ca.w, cb2.x, cb2.y, cb2.z, cb2.w}, sn[8] = {sa.x, sa.y, sa.z, sa.w, sb.x, sb.y, sb.z, sb.w};
;             const float mv[8] = {bf_lo(mv4.x), bf_hi(mv4.x), bf_lo(mv4.y), bf_hi(mv4.y), bf_lo(mv4.z), bf_hi(mv4.z), bf_lo(mv4.w), bf_hi(mv4.w)};
;             const float pp[8] = {bf_lo(pv4.x), bf_hi(pv4.x), bf_lo(pv4.y), bf_hi(pv4.y), bf_lo(pv4.z), bf_hi(pv4.z), bf_lo(pv4.w), bf_hi(pv4.w)};
;             const bool roped = fq < 2; const float sg = (fq == 0) ? -1.f : 1.f; float o[8];
; #pragma unroll
;             for (int e = 0; e < 8; ++e) o[e] = (roped ? (mv[e] * cs[e] + sg * pp[e] * sn[e]) : mv[e]) * QS;
;             q16f[sub][0] = pack_p(o);
;             gs4[sub] = sigm(bf1(P[tok4 * PP + PC_NG + head4 * 3 + 1]));
.LBB0_809:
	s_or_b64 exec, exec, s[0:1]
	v_bfe_u32 v12, v224, 2, 2
	v_or_b32_e32 v211, s97, v12
	v_or_b32_e32 v10, s76, v211
	v_mov_b64_e32 v[2:3], s[86:87]
	v_mad_u64_u32 v[4:5], s[0:1], v10, s67, v[2:3]
	v_mov_b32_e32 v179, v1
	v_lshl_add_u64 v[6:7], v[4:5], 0, v[178:179]
	s_bcnt1_i32_b64 s2, vcc
	v_add_co_u32_e32 v6, vcc, 0x1000, v6
	s_waitcnt lgkmcnt(0)
	s_add_i32 s3, s3, s2
	s_nop 0
	v_addc_co_u32_e32 v7, vcc, 0, v7, vcc
	global_load_ushort v251, v[6:7], off offset:2562
	v_or_b32_e32 v6, 4, v10
	v_mad_u64_u32 v[2:3], s[0:1], v6, s67, v[2:3]
	v_lshl_add_u64 v[8:9], v[2:3], 0, v[178:179]
	v_add_co_u32_e32 v8, vcc, 0x1000, v8
	v_mov_b64_e32 v[246:247], 0x200
	s_nop 0
	v_addc_co_u32_e32 v9, vcc, 0, v9, vcc
	global_load_ushort v210, v[8:9], off offset:2562
	v_mov_b64_e32 v[216:217], 0xaff
	v_ashrrev_i32_e32 v245, 4, v224
	s_cmp_eq_u32 s3, 0
	v_lshlrev_b64 v[228:229], 4, v[224:225]
	v_lshlrev_b32_e32 v226, 1, v186
	s_cbranch_scc1 .LBB0_865
	v_lshlrev_b32_e32 v232, 3, v245
	v_ashrrev_i32_e32 v233, 31, v232
	v_mov_b32_e32 v227, v1
	v_lshl_add_u64 v[18:19], v[4:5], 0, v[226:227]
	v_lshlrev_b64 v[4:5], 1, v[232:233]
	v_lshl_add_u64 v[8:9], v[18:19], 0, v[4:5]
	global_load_dwordx4 v[14:17], v[8:9], off offset:3136
	v_bitop3_b32 v13, v232, 8, v232 bitop3:0xc
	v_mov_b32_e32 v11, v1
	v_lshlrev_b64 v[10:11], 6, v[10:11]
	v_lshl_add_u64 v[10:11], s[78:79], 0, v[10:11]
	s_lshl_b64 s[0:1], s[22:23], 4
	s_add_u32 s10, s90, s0
	s_addc_u32 s11, s91, s1
	s_add_u32 s4, s94, s0
	s_addc_u32 s5, s95, s1
	v_cmp_gt_u32_e64 s[0:1], 16, v224
	v_cmp_gt_i32_e32 vcc, 2, v245
	v_mov_b32_e32 v7, v1
	v_lshlrev_b64 v[6:7], 6, v[6:7]
	v_lshl_add_u64 v[6:7], s[78:79], 0, v[6:7]
	v_lshl_add_u64 v[234:235], s[4:5], 0, v[228:229]
	v_lshl_add_u64 v[230:231], s[10:11], 0, v[228:229]
	s_lshl_b32 s3, s3, 1
	s_mov_b32 s2, 4
	s_add_i32 s18, s3, -1
	s_waitcnt vmcnt(0)
	v_lshlrev_b32_e32 v20, 16, v14
	v_and_b32_e32 v21, 0xffff0000, v14
	v_lshlrev_b32_e32 v14, 16, v15
	v_and_b32_e32 v15, 0xffff0000, v15
	v_pk_mul_f32 v[14:15], v[14:15], s[38:39] op_sel_hi:[1,0]
	v_pk_mul_f32 v[20:21], v[20:21], s[38:39] op_sel_hi:[1,0]
	v_cvt_pk_bf16_f32 v99, v14, v15
	v_lshlrev_b32_e32 v14, 16, v16
	v_and_b32_e32 v15, 0xffff0000, v16
	v_pk_mul_f32 v[14:15], v[14:15], s[38:39] op_sel_hi:[1,0]
	v_cvt_pk_bf16_f32 v98, v20, v21
	v_cvt_pk_bf16_f32 v100, v14, v15
	v_lshlrev_b32_e32 v14, 16, v17
	v_and_b32_e32 v15, 0xffff0000, v17
	v_pk_mul_f32 v[14:15], v[14:15], s[38:39] op_sel_hi:[1,0]
	s_nop 0
	v_cvt_pk_bf16_f32 v101, v14, v15
	global_load_dwordx4 v[14:17], v[8:9], off offset:3072
	v_lshlrev_b32_e32 v8, 1, v13
	v_mov_b32_e32 v9, v1
	v_lshl_add_u64 v[18:19], v[18:19], 0, v[8:9]
	global_load_dwordx4 v[18:21], v[18:19], off offset:3072
	s_nop 0
	global_load_dwordx4 v[22:25], v[10:11], off offset:16
	global_load_dwordx4 v[26:29], v[10:11], off offset:48
	global_load_dwordx4 v[30:33], v[10:11], off
	global_load_dwordx4 v[34:37], v[10:11], off offset:32
	s_waitcnt vmcnt(5)
	v_lshlrev_b32_e32 v10, 16, v14
	v_lshlrev_b32_e32 v44, 16, v17
	v_and_b32_e32 v46, 0xffff0000, v17
	v_and_b32_e32 v14, 0xffff0000, v14
	s_waitcnt vmcnt(4)
	v_lshlrev_b32_e32 v11, 16, v18
	v_and_b32_e32 v13, 0xffff0000, v18
	v_lshlrev_b32_e32 v17, 16, v19
	v_and_b32_e32 v41, 0xffff0000, v19
	v_cndmask_b32_e64 v11, v11, -v11, s[0:1]
	s_waitcnt vmcnt(1)
	v_mov_b32_e32 v18, v30
	s_waitcnt vmcnt(0)
	v_mov_b32_e32 v19, v34
	v_pk_mul_f32 v[18:19], v[18:19], v[10:11]
	v_lshlrev_b32_e32 v38, 16, v15
	v_add_f32_e32 v11, v18, v19
	v_and_b32_e32 v40, 0xffff0000, v15
	v_cndmask_b32_e32 v10, v10, v11, vcc
	v_cndmask_b32_e64 v15, v13, -v13, s[0:1]
	v_mov_b32_e32 v34, v31
	v_mul_f32_e32 v18, 0x3e38aa3b, v10
	v_pk_mul_f32 v[10:11], v[34:35], v[14:15]
	v_cndmask_b32_e64 v39, v17, -v17, s[0:1]
	v_add_f32_e32 v10, v10, v11
	v_cndmask_b32_e32 v10, v14, v10, vcc
	v_mul_f32_e32 v13, 0x3e38aa3b, v10
	v_mov_b32_e32 v10, v32
	v_mov_b32_e32 v11, v36
	v_pk_mul_f32 v[10:11], v[10:11], v[38:39]
	v_cndmask_b32_e64 v41, v41, -v41, s[0:1]
	v_add_f32_e32 v10, v10, v11
	v_cndmask_b32_e32 v10, v38, v10, vcc
	v_mov_b32_e32 v36, v33
	v_mul_f32_e32 v14, 0x3e38aa3b, v10
	v_pk_mul_f32 v[10:11], v[36:37], v[40:41]
	v_lshlrev_b32_e32 v43, 16, v20
	v_add_f32_e32 v10, v10, v11
	v_cndmask_b32_e32 v10, v40, v10, vcc
	v_lshlrev_b32_e32 v42, 16, v16
	v_mul_f32_e32 v15, 0x3e38aa3b, v10
	v_cndmask_b32_e64 v43, v43, -v43, s[0:1]
	v_mov_b32_e32 v10, v22
	v_mov_b32_e32 v11, v26
	v_pk_mul_f32 v[10:11], v[10:11], v[42:43]
	v_and_b32_e32 v20, 0xffff0000, v20
	v_add_f32_e32 v10, v10, v11
	v_and_b32_e32 v16, 0xffff0000, v16
	v_cndmask_b32_e32 v10, v42, v10, vcc
	v_cndmask_b32_e64 v17, v20, -v20, s[0:1]
	v_mov_b32_e32 v26, v23
	v_mul_f32_e32 v19, 0x3e38aa3b, v10
	v_pk_mul_f32 v[10:11], v[26:27], v[16:17]
	v_lshlrev_b32_e32 v45, 16, v21
	v_add_f32_e32 v10, v10, v11
	v_cndmask_b32_e32 v10, v16, v10, vcc
	v_mul_f32_e32 v16, 0x3e38aa3b, v10
	v_cndmask_b32_e64 v45, v45, -v45, s[0:1]
	v_mov_b32_e32 v10, v24
	v_mov_b32_e32 v11, v28
	v_pk_mul_f32 v[10:11], v[10:11], v[44:45]
	v_and_b32_e32 v21, 0xffff0000, v21
	v_add_f32_e32 v10, v10, v11
	v_cndmask_b32_e32 v10, v44, v10, vcc
	v_cndmask_b32_e64 v47, v21, -v21, s[0:1]
	v_mov_b32_e32 v28, v25
	v_mul_f32_e32 v17, 0x3e38aa3b, v10
	v_pk_mul_f32 v[10:11], v[28:29], v[46:47]
	v_cvt_pk_bf16_f32 v103, v14, v15
	v_add_f32_e32 v10, v10, v11
	v_cndmask_b32_e32 v10, v46, v10, vcc
	v_mul_f32_e32 v10, 0x3e38aa3b, v10
	v_cvt_pk_bf16_f32 v105, v17, v10
	v_lshl_add_u64 v[10:11], v[2:3], 0, v[226:227]
	v_lshl_add_u64 v[14:15], v[10:11], 0, v[4:5]
	global_load_dwordx4 v[2:5], v[14:15], off offset:3136
	v_cvt_pk_bf16_f32 v104, v19, v16
	v_lshl_add_u64 v[8:9], v[10:11], 0, v[8:9]
	v_cvt_pk_bf16_f32 v102, v18, v13
	global_load_dwordx4 v[8:11], v[8:9], off offset:3072
	s_waitcnt vmcnt(1)
; #define LAS __attribute__((address_space(3)))
; __device__ __forceinline__ float bf_lo(unsigned u) { return __uint_as_float(u << 16); }
; __device__ __forceinline__ float bf_hi(unsigned u) { return __uint_as_float(u & 0xffff0000u); }
; __device__ __forceinline__ float bf1(bf16_t u) { return __uint_as_float(((unsigned)u) << 16); }
; __device__ __forceinline__ unsigned flash16_entry(int s, const LAS unsigned* list) {
;     const unsigned e = (unsigned)__builtin_amdgcn_readfirstlane((int)list[s >> 1]);
;     return (e & 0xffff0000u) | (2u * (e & 0xffffu) + (unsigned)(s & 1));
; }
; __device__ __forceinline__ void flash16_run(const bf16x8* kb, const bf16x8* vb, const bf16x8 (&qa)[2], const bf16x8 (&qb)[2], int nsteps, const LAS unsigned* list, int tq, int t0, int qi4, int fq, ...
;     if (nsteps <= 0) return;
;     bf16x8 kA[4], vA[4], kB[4], vB[4], kC[4], vC[4]; unsigned eA, eB, eC;
;     ...
;     F16_LOAD(0, kA, vA, eA); F16_LOAD(1, kB, vB, eB);
; __device__ __forceinline__ void nsa_tile(const Ctx& C, int b, int g, int t0) {
;     ...
;             const u32x4 mv4 = *(const u32x4*)(qp + 8 * fq), pv4 = *(const u32x4*)(qp + 8 * ((fq ^ 1) & 1));
;             const float* rt = (const float*)(C.ws + WS_ROPE) + tok4 * 16;
;             const f32x4 ca = *(const f32x4*)rt, cb2 = *(const f32x4*)(rt + 4), sa = *(const f32x4*)(rt + 8), sb = *(const f32x4*)(rt + 12);
;             const float cs[8] = {ca.x, ca.y, ca.z, ca.w, cb2.x, cb2.y, cb2.z, cb2.w}, sn[8] = {sa.x, sa.y, sa.z, sa.w, sb.x, sb.y, sb.z, sb.w};
;             const float mv[8] = {bf_lo(mv4.x), bf_hi(mv4.x), bf_lo(mv4.y), bf_hi(mv4.y), bf_lo(mv4.z), bf_hi(mv4.z), bf_lo(mv4.w), bf_hi(mv4.w)};
;             const float pp[8] = {bf_lo(pv4.x), bf_hi(pv4.x), bf_lo(pv4.y), bf_hi(pv4.y), bf_lo(pv4.z), bf_hi(pv4.z), bf_lo(pv4.w), bf_hi(pv4.w)};
;             const bool roped = fq < 2; const float sg = (fq == 0) ? -1.f : 1.f; float o[8];
; #pragma unroll
;             for (int e = 0; e < 8; ++e) o[e] = (roped ? (mv[e] * cs[e] + sg * pp[e] * sn[e]) : mv[e]) * QS;
;             q16f[sub][0] = pack_p(o);
;             gs4[sub] = sigm(bf1(P[tok4 * PP + PC_NG + head4 * 3 + 1]));
;         }
;         float ma = -1e30f, la = 0.f, mb = -1e30f, lb = 0.f; f32x4v Oa[4], Ob[4];
; #pragma unroll
;         for (int dt = 0; dt < 4; ++dt) { Oa[dt] = (f32x4v){0.f, 0.f, 0.f, 0.f}; Ob[dt] = (f32x4v){0.f, 0.f, 0.f, 0.f}; }
	v_lshlrev_b32_e32 v16, 16, v2
	v_and_b32_e32 v17, 0xffff0000, v2
	v_lshlrev_b32_e32 v2, 16, v3
	v_and_b32_e32 v3, 0xffff0000, v3
	v_pk_mul_f32 v[2:3], v[2:3], s[38:39] op_sel_hi:[1,0]
	v_pk_mul_f32 v[16:17], v[16:17], s[38:39] op_sel_hi:[1,0]
	v_cvt_pk_bf16_f32 v107, v2, v3
	v_lshlrev_b32_e32 v2, 16, v4
	v_and_b32_e32 v3, 0xffff0000, v4
	v_pk_mul_f32 v[2:3], v[2:3], s[38:39] op_sel_hi:[1,0]
	v_cvt_pk_bf16_f32 v106, v16, v17
	v_cvt_pk_bf16_f32 v108, v2, v3
	v_lshlrev_b32_e32 v2, 16, v5
	v_and_b32_e32 v3, 0xffff0000, v5
	v_pk_mul_f32 v[2:3], v[2:3], s[38:39] op_sel_hi:[1,0]
	s_waitcnt vmcnt(0)
	v_and_b32_e32 v13, 0xffff0000, v9
	v_cvt_pk_bf16_f32 v109, v2, v3
	global_load_dwordx4 v[2:5], v[14:15], off offset:3072
	s_nop 0
	global_load_dwordx4 v[14:17], v[6:7], off offset:16
	global_load_dwordx4 v[18:21], v[6:7], off offset:48
	global_load_dwordx4 v[22:25], v[6:7], off
	global_load_dwordx4 v[26:29], v[6:7], off offset:32
	v_lshlrev_b32_e32 v7, 16, v8
	v_lshlrev_b32_e32 v35, 16, v10
	v_and_b32_e32 v10, 0xffff0000, v10
	v_lshlrev_b32_e32 v37, 16, v11
	v_and_b32_e32 v11, 0xffff0000, v11
	v_cndmask_b32_e64 v7, v7, -v7, s[0:1]
	v_cndmask_b32_e64 v33, v13, -v13, s[0:1]
	v_cndmask_b32_e64 v35, v35, -v35, s[0:1]
	v_cndmask_b32_e64 v37, v37, -v37, s[0:1]
	v_cndmask_b32_e64 v39, v11, -v11, s[0:1]
	s_waitcnt vmcnt(4)
	v_lshlrev_b32_e32 v6, 16, v2
	v_lshlrev_b32_e32 v30, 16, v3
	v_and_b32_e32 v32, 0xffff0000, v3
	v_lshlrev_b32_e32 v36, 16, v5
	v_and_b32_e32 v38, 0xffff0000, v5
	v_and_b32_e32 v3, 0xffff0000, v8
	v_lshlrev_b32_e32 v5, 16, v9
	s_waitcnt vmcnt(1)
	v_mov_b32_e32 v8, v22
	s_waitcnt vmcnt(0)
	v_mov_b32_e32 v9, v26
	v_pk_mul_f32 v[8:9], v[8:9], v[6:7]
	v_and_b32_e32 v2, 0xffff0000, v2
	v_add_f32_e32 v7, v8, v9
	v_cndmask_b32_e32 v6, v6, v7, vcc
	v_cndmask_b32_e64 v3, v3, -v3, s[0:1]
	v_mov_b32_e32 v26, v23
	v_mul_f32_e32 v8, 0x3e38aa3b, v6
	v_pk_mul_f32 v[6:7], v[26:27], v[2:3]
	v_cndmask_b32_e64 v31, v5, -v5, s[0:1]
	v_add_f32_e32 v3, v6, v7
	v_cndmask_b32_e32 v2, v2, v3, vcc
	v_mul_f32_e32 v6, 0x3e38aa3b, v2
	v_mov_b32_e32 v2, v24
	v_mov_b32_e32 v3, v28
	v_pk_mul_f32 v[2:3], v[2:3], v[30:31]
	v_mov_b32_e32 v28, v25
	v_add_f32_e32 v2, v2, v3
	v_cndmask_b32_e32 v2, v30, v2, vcc
	v_mul_f32_e32 v7, 0x3e38aa3b, v2
	v_pk_mul_f32 v[2:3], v[28:29], v[32:33]
	v_lshlrev_b32_e32 v34, 16, v4
	v_add_f32_e32 v2, v2, v3
	v_cndmask_b32_e32 v2, v32, v2, vcc
	v_mul_f32_e32 v9, 0x3e38aa3b, v2
	v_mov_b32_e32 v2, v14
	v_mov_b32_e32 v3, v18
	v_pk_mul_f32 v[2:3], v[2:3], v[34:35]
	v_and_b32_e32 v4, 0xffff0000, v4
	v_add_f32_e32 v2, v2, v3
	v_cndmask_b32_e32 v2, v34, v2, vcc
	v_cndmask_b32_e64 v5, v10, -v10, s[0:1]
	v_mov_b32_e32 v18, v15
	v_mul_f32_e32 v13, 0x3e38aa3b, v2
	v_pk_mul_f32 v[2:3], v[18:19], v[4:5]
	v_cvt_pk_bf16_f32 v110, v8, v6
	v_add_f32_e32 v2, v2, v3
	v_cndmask_b32_e32 v2, v4, v2, vcc
	v_mul_f32_e32 v4, 0x3e38aa3b, v2
	v_mov_b32_e32 v2, v16
	v_mov_b32_e32 v3, v20
	v_pk_mul_f32 v[2:3], v[2:3], v[36:37]
	v_mov_b32_e32 v20, v17
	v_add_f32_e32 v2, v2, v3
	v_cndmask_b32_e32 v2, v36, v2, vcc
	v_mul_f32_e32 v5, 0x3e38aa3b, v2
	v_pk_mul_f32 v[2:3], v[20:21], v[38:39]
	v_mov_b32_e32 v6, s73
	v_add_f32_e32 v2, v2, v3
	v_cndmask_b32_e32 v2, v38, v2, vcc
	v_mul_f32_e32 v2, 0x3e38aa3b, v2
	v_cvt_pk_bf16_f32 v113, v5, v2
	v_cvt_pk_bf16_f32 v112, v13, v4
	v_cvt_pk_bf16_f32 v111, v7, v9
	v_lshlrev_b32_e64 v225, v12, 1
	v_or_b32_e32 v227, 4, v211
	v_mov_b32_e32 v18, v1
	v_mov_b32_e32 v19, v1
	v_mov_b32_e32 v20, v1
	v_mov_b32_e32 v21, v1
	v_mov_b32_e32 v22, v1
	v_mov_b32_e32 v23, v1
	v_mov_b32_e32 v24, v1
	v_mov_b32_e32 v25, v1
	v_mov_b32_e32 v26, v1
	v_mov_b32_e32 v27, v1
	v_mov_b32_e32 v28, v1
	v_mov_b32_e32 v29, v1
	v_mov_b32_e32 v30, v1
	v_mov_b32_e32 v31, v1
	v_mov_b32_e32 v32, v1
	v_mov_b32_e32 v33, v1
	v_mov_b32_e32 v34, v1
	v_mov_b32_e32 v35, v1
	v_mov_b32_e32 v36, v1
	v_mov_b32_e32 v37, v1
	v_mov_b32_e32 v38, v1
	v_mov_b32_e32 v39, v1
	v_mov_b32_e32 v40, v1
	v_mov_b32_e32 v41, v1
	v_mov_b32_e32 v42, v1
	v_mov_b32_e32 v43, v1
	v_mov_b32_e32 v44, v1
	v_mov_b32_e32 v45, v1
	v_mov_b32_e32 v46, v1
	v_mov_b32_e32 v47, v1
	v_mov_b32_e32 v48, v1
	v_mov_b32_e32 v49, v1
	v_mov_b32_e32 v236, v249
	v_mov_b32_e32 v237, v249
	v_mov_b32_e32 v94, v249
	v_mov_b32_e32 v95, v249
	v_mov_b32_e32 v240, 0
	v_mov_b32_e32 v241, 0
	v_mov_b32_e32 v238, 0
	v_mov_b32_e32 v239, 0
	s_mov_b32 s1, 0
	s_min_i32 s1, s1, s18
	s_lshl_b32 s10, s1, 1
	s_and_b32 s10, s10, -4
	s_add_i32 s10, s73, s10
	v_mov_b32_e32 v55, s10
	ds_read_b32 v54, v55
	s_waitcnt lgkmcnt(0)
; #define LAS __attribute__((address_space(3)))
; __device__ __forceinline__ f32x4v mfma16(bf16x8 a, bf16x8 b, f32x4v c) { return __builtin_amdgcn_mfma_f32_16x16x32_bf16(a, b, c, 0, 0, 0); }
; __device__ __forceinline__ float xq_max(float v) { const auto r = __builtin_amdgcn_permlane16_swap(__float_as_uint(v), __float_as_uint(v), false, false); return xhalf_max(fmaxf(__uint_as_float(r[0]), __uint_as_float(r[1]))); }
; #define F16_LOAD(S, KF, VF, E) do { const int sn_ = ((S) < nsteps) ? (S) : nsteps - 1; E = flash16_entry(sn_, list); const size_t go_ = (size_t)(E & 0xffffu) * 256; \
;         flash16_load(kb + go_, vb + go_, KF, VF); } while (0)
; __device__ __forceinline__ void flash16_compute(bool domask, const bf16x8 (&kf)[4], const bf16x8 (&vf)[4], const bf16x8 (&q)[2], int x0, unsigned span, float& m, float& l, f32x4v (&O)[4]) {
;     f32x4v s0 = {0.f, 0.f, 0.f, 0.f}, s1 = {0.f, 0.f, 0.f, 0.f};
;     __builtin_amdgcn_s_setprio(1);
;     s0 = mfma16(kf[0], q[0], s0); s1 = mfma16(kf[2], q[0], s1);
;     s0 = mfma16(kf[1], q[1], s0); s1 = mfma16(kf[3], q[1], s1);
;     __builtin_amdgcn_s_setprio(0);
;     float sc[8] = {s0[0], s0[1], s0[2], s0[3], s1[0], s1[1], s1[2], s1[3]};
;     if (domask) {
; #pragma unroll
;         for (int j = 0; j < 8; ++j) sc[j] = ((unsigned)(x0 + j) <= span) ? sc[j] : -1e30f;
;     }
;     float mx = fmaxf(fmaxf(fmaxf(sc[0], sc[1]), fmaxf(sc[2], sc[3])), fmaxf(fmaxf(sc[4], sc[5]), fmaxf(sc[6], sc[7])));
;     mx = xq_max(mx);
; __device__ __forceinline__ void flash16_run(const bf16x8* kb, const bf16x8* vb, const bf16x8 (&qa)[2], const bf16x8 (&qb)[2], int nsteps, const LAS unsigned* list, int tq, int t0, int qi4, int fq, ...
;     if (nsteps <= 0) return;
;     bf16x8 kA[4], vA[4], kB[4], vB[4], kC[4], vC[4]; unsigned eA, eB, eC;
;     ...
;     F16_LOAD(0, kA, vA, eA); F16_LOAD(1, kB, vB, eB);
; #pragma unroll 1
;     for (int s = 0; s < nsteps; s += 3) {
;         F16_LOAD(s + 2, kC, vC, eC); F16_COMP(kA, vA, eA); if (s + 1 >= nsteps) break;
;         F16_LOAD(s + 3, kA, vA, eA); F16_COMP(kB, vB, eB); if (s + 2 >= nsteps) break;
;         F16_LOAD(s + 4, kB, vB, eB); F16_COMP(kC, vC, eC);
	v_readfirstlane_b32 s0, v54
	s_and_b32 s5, s1, 1
	s_lshl_b32 s6, s0, 1
	s_and_b32 s6, s6, 0x1fffe
	s_or_b32 s6, s6, s5
	s_and_b32 s0, s0, 0xffff0000
	s_or_b32 s16, s0, s6
	s_lshl_b32 s6, s6, 12
	v_lshl_add_u64 v[56:57], v[230:231], 0, s[6:7]
	v_lshl_add_u64 v[58:59], v[234:235], 0, s[6:7]
	global_load_dwordx4 v[114:117], v[56:57], off
	global_load_dwordx4 v[118:121], v[56:57], off offset:1024
	global_load_dwordx4 v[122:125], v[56:57], off offset:2048
	global_load_dwordx4 v[126:129], v[56:57], off offset:3072
	global_load_dwordx4 v[130:133], v[58:59], off
	global_load_dwordx4 v[134:137], v[58:59], off offset:1024
	global_load_dwordx4 v[138:141], v[58:59], off offset:2048
	global_load_dwordx4 v[142:145], v[58:59], off offset:3072
	s_mov_b32 s1, 1
	s_min_i32 s1, s1, s18
	s_lshl_b32 s10, s1, 1
	s_and_b32 s10, s10, -4
	s_add_i32 s10, s73, s10
	v_mov_b32_e32 v55, s10
	ds_read_b32 v54, v55
	s_waitcnt lgkmcnt(0)
	v_readfirstlane_b32 s0, v54
	s_and_b32 s5, s1, 1
	s_lshl_b32 s6, s0, 1
	s_and_b32 s6, s6, 0x1fffe
	s_or_b32 s6, s6, s5
	s_and_b32 s0, s0, 0xffff0000
	s_or_b32 s17, s0, s6
	s_lshl_b32 s6, s6, 12
	v_lshl_add_u64 v[56:57], v[230:231], 0, s[6:7]
	v_lshl_add_u64 v[58:59], v[234:235], 0, s[6:7]
	global_load_dwordx4 v[146:149], v[56:57], off
	global_load_dwordx4 v[150:153], v[56:57], off offset:1024
	global_load_dwordx4 v[154:157], v[56:57], off offset:2048
	global_load_dwordx4 v[158:161], v[56:57], off offset:3072
	global_load_dwordx4 v[162:165], v[58:59], off
	global_load_dwordx4 v[166:169], v[58:59], off offset:1024
	global_load_dwordx4 v[170:173], v[58:59], off offset:2048
	global_load_dwordx4 v[174:177], v[58:59], off offset:3072
	s_mov_b32 s1, 2
	s_min_i32 s1, s1, s18
	s_lshl_b32 s10, s1, 1
	s_and_b32 s10, s10, -4
	s_add_i32 s10, s73, s10
	v_mov_b32_e32 v55, s10
	ds_read_b32 v54, v55
	s_waitcnt lgkmcnt(0)
	v_readfirstlane_b32 s0, v54
	s_and_b32 s5, s1, 1
	s_lshl_b32 s6, s0, 1
	s_and_b32 s6, s6, 0x1fffe
	s_or_b32 s6, s6, s5
	s_and_b32 s0, s0, 0xffff0000
	s_or_b32 s19, s0, s6
	s_lshl_b32 s6, s6, 12
	v_lshl_add_u64 v[56:57], v[230:231], 0, s[6:7]
	v_lshl_add_u64 v[58:59], v[234:235], 0, s[6:7]
	global_load_dwordx4 v[178:181], v[56:57], off
	global_load_dwordx4 v[182:185], v[56:57], off offset:1024
	global_load_dwordx4 v[186:189], v[56:57], off offset:2048
	global_load_dwordx4 v[190:193], v[56:57], off offset:3072
	global_load_dwordx4 v[194:197], v[58:59], off
	global_load_dwordx4 v[198:201], v[58:59], off offset:1024
	global_load_dwordx4 v[202:205], v[58:59], off offset:2048
	global_load_dwordx4 v[206:209], v[58:59], off offset:3072
	s_mov_b32 s1, 3
	s_min_i32 s1, s1, s18
	s_lshl_b32 s10, s1, 1
	s_and_b32 s10, s10, -4
	s_add_i32 s10, s73, s10
	v_mov_b32_e32 v55, s10
	ds_read_b32 v54, v55
	s_mov_b32 s2, 0
.Lsel_step_A:
	s_add_i32 s1, s2, 3
	s_min_i32 s1, s1, s18
	s_waitcnt lgkmcnt(0)
	v_readfirstlane_b32 s0, v54
	s_and_b32 s5, s1, 1
	s_lshl_b32 s6, s0, 1
	s_and_b32 s6, s6, 0x1fffe
	s_or_b32 s6, s6, s5
	s_and_b32 s0, s0, 0xffff0000
	s_or_b32 s4, s0, s6
	s_lshl_b32 s6, s6, 12
	v_lshl_add_u64 v[56:57], v[230:231], 0, s[6:7]
	v_lshl_add_u64 v[58:59], v[234:235], 0, s[6:7]
	global_load_dwordx4 v[62:65], v[56:57], off
	global_load_dwordx4 v[66:69], v[56:57], off offset:1024
	global_load_dwordx4 v[70:73], v[56:57], off offset:2048
	global_load_dwordx4 v[74:77], v[56:57], off offset:3072
	global_load_dwordx4 v[78:81], v[58:59], off
	global_load_dwordx4 v[82:85], v[58:59], off offset:1024
	global_load_dwordx4 v[86:89], v[58:59], off offset:2048
	global_load_dwordx4 v[90:93], v[58:59], off offset:3072
	s_add_i32 s1, s2, 4
	s_min_i32 s1, s1, s18
	s_lshl_b32 s10, s1, 1
	s_and_b32 s10, s10, -4
	s_add_i32 s10, s73, s10
	v_mov_b32_e32 v55, s10
	ds_read_b32 v54, v55
	s_and_b32 s10, s16, 0xffff
	s_lshl_b32 s10, s10, 5
	s_or_b32 s11, s10, 31
	s_cmp_le_u32 s11, s97
	s_cselect_b32 s22, 1, 0
	s_bfe_u32 s12, s16, 0x40010
	s_lshr_b32 s13, s16, 20
	s_waitcnt vmcnt(24)
	s_cmp_eq_u32 s12, 0
	s_cbranch_scc1 .Lsel_skip_Aa
	v_and_b32_e32 v14, s12, v225
	v_cmp_eq_u32_e32 vcc, 0, v14
	s_cmp_eq_u32 s22, 0
	s_cbranch_scc1 .Lsel_slow_Aa
	v_cndmask_b32_e32 v10, 0, v249, vcc
	v_cndmask_b32_e32 v11, 0, v249, vcc
	v_cndmask_b32_e32 v12, 0, v249, vcc
	v_cndmask_b32_e32 v13, 0, v249, vcc
	s_nop 1
	v_mfma_f32_16x16x32_bf16 v[2:5], v[114:117], v[102:105], v[10:13]
	v_mfma_f32_16x16x32_bf16 v[6:9], v[122:125], v[102:105], v[10:13]
.Lsel_qk2_Aa:
	v_mfma_f32_16x16x32_bf16 v[2:5], v[118:121], v[98:101], v[2:5]
	v_mfma_f32_16x16x32_bf16 v[6:9], v[126:129], v[98:101], v[6:9]
	s_nop 6
	v_max3_f32 v14, v2, v3, v4
	v_max3_f32 v14, v14, v5, v6
	v_max3_f32 v14, v14, v7, v8
	v_max_f32_e32 v14, v14, v9
	v_mov_b32_e32 v16, v14
	s_nop 1
	v_permlane16_swap_b32_e32 v14, v16
	v_max_f32_e32 v14, v14, v16
	v_mov_b32_e32 v16, v14
	s_nop 1
	v_permlane32_swap_b32_e32 v14, v16
	v_max_f32_e32 v14, v14, v16
	v_cmp_gt_f32_e32 vcc, v14, v94
	s_cbranch_vccnz .Lsel_upd_Aa

; __device__ __forceinline__ float xq_max(float v) { const auto r = __builtin_amdgcn_permlane16_swap(__float_as_uint(v), __float_as_uint(v), false, false); return xhalf_max(fmaxf(__uint_as_float(r[0]), __uint_as_float(r[1]))); }
; __device__ __forceinline__ void flash16_compute(bool domask, const bf16x8 (&kf)[4], const bf16x8 (&vf)[4], const bf16x8 (&q)[2], int x0, unsigned span, float& m, float& l, f32x4v (&O)[4]) {
;     ...
;     float mx = fmaxf(fmaxf(fmaxf(sc[0], sc[1]), fmaxf(sc[2], sc[3])), fmaxf(fmaxf(sc[4], sc[5]), fmaxf(sc[6], sc[7])));
;     mx = xq_max(mx);
;     const bool upd = mx > m + SM_THR;
;     if (__ballot(upd) != 0ull) {
.Lsel_qk2_Ab:
	v_mfma_f32_16x16x32_bf16 v[2:5], v[118:121], v[106:109], v[2:5]
	v_mfma_f32_16x16x32_bf16 v[6:9], v[126:129], v[106:109], v[6:9]
	s_nop 6
	v_max3_f32 v14, v2, v3, v4
	v_max3_f32 v14, v14, v5, v6
	v_max3_f32 v14, v14, v7, v8
	v_max_f32_e32 v14, v14, v9
	v_mov_b32_e32 v16, v14
	s_nop 1
	v_permlane16_swap_b32_e32 v14, v16
	v_max_f32_e32 v14, v14, v16
	v_mov_b32_e32 v16, v14
	s_nop 1
	v_permlane32_swap_b32_e32 v14, v16
	v_max_f32_e32 v14, v14, v16
	v_cmp_gt_f32_e32 vcc, v14, v95
	s_cbranch_vccnz .Lsel_upd_Ab

; __device__ __forceinline__ f32x4v mfma16(bf16x8 a, bf16x8 b, f32x4v c) { return __builtin_amdgcn_mfma_f32_16x16x32_bf16(a, b, c, 0, 0, 0); }
; __device__ __forceinline__ float xq_max(float v) { const auto r = __builtin_amdgcn_permlane16_swap(__float_as_uint(v), __float_as_uint(v), false, false); return xhalf_max(fmaxf(__uint_as_float(r[0]), __uint_as_float(r[1]))); }
; #define F16_LOAD(S, KF, VF, E) do { const int sn_ = ((S) < nsteps) ? (S) : nsteps - 1; E = flash16_entry(sn_, list); const size_t go_ = (size_t)(E & 0xffffu) * 256; \
;         flash16_load(kb + go_, vb + go_, KF, VF); } while (0)
; __device__ __forceinline__ void flash16_compute(bool domask, const bf16x8 (&kf)[4], const bf16x8 (&vf)[4], const bf16x8 (&q)[2], int x0, unsigned span, float& m, float& l, f32x4v (&O)[4]) {
;     f32x4v s0 = {0.f, 0.f, 0.f, 0.f}, s1 = {0.f, 0.f, 0.f, 0.f};
;     __builtin_amdgcn_s_setprio(1);
;     s0 = mfma16(kf[0], q[0], s0); s1 = mfma16(kf[2], q[0], s1);
;     s0 = mfma16(kf[1], q[1], s0); s1 = mfma16(kf[3], q[1], s1);
;     __builtin_amdgcn_s_setprio(0);
;     float sc[8] = {s0[0], s0[1], s0[2], s0[3], s1[0], s1[1], s1[2], s1[3]};
;     if (domask) {
; #pragma unroll
;         for (int j = 0; j < 8; ++j) sc[j] = ((unsigned)(x0 + j) <= span) ? sc[j] : -1e30f;
;     }
;     float mx = fmaxf(fmaxf(fmaxf(sc[0], sc[1]), fmaxf(sc[2], sc[3])), fmaxf(fmaxf(sc[4], sc[5]), fmaxf(sc[6], sc[7])));
;     mx = xq_max(mx);
; __device__ __forceinline__ void flash16_run(const bf16x8* kb, const bf16x8* vb, const bf16x8 (&qa)[2], const bf16x8 (&qb)[2], int nsteps, const LAS unsigned* list, int tq, int t0, int qi4, int fq, ...
;     ...
;     F16_LOAD(0, kA, vA, eA); F16_LOAD(1, kB, vB, eB);
; #pragma unroll 1
;     for (int s = 0; s < nsteps; s += 3) {
;         F16_LOAD(s + 2, kC, vC, eC); F16_COMP(kA, vA, eA); if (s + 1 >= nsteps) break;
;         F16_LOAD(s + 3, kA, vA, eA); F16_COMP(kB, vB, eB); if (s + 2 >= nsteps) break;
;         F16_LOAD(s + 4, kB, vB, eB); F16_COMP(kC, vC, eC);
.Lsel_step_B:
	s_add_i32 s1, s2, 3
	s_min_i32 s1, s1, s18
	s_waitcnt lgkmcnt(0)
	v_readfirstlane_b32 s0, v54
	s_and_b32 s5, s1, 1
	s_lshl_b32 s6, s0, 1
	s_and_b32 s6, s6, 0x1fffe
	s_or_b32 s6, s6, s5
	s_and_b32 s0, s0, 0xffff0000
	s_or_b32 s16, s0, s6
	s_lshl_b32 s6, s6, 12
	v_lshl_add_u64 v[56:57], v[230:231], 0, s[6:7]
	v_lshl_add_u64 v[58:59], v[234:235], 0, s[6:7]
	global_load_dwordx4 v[114:117], v[56:57], off
	global_load_dwordx4 v[118:121], v[56:57], off offset:1024
	global_load_dwordx4 v[122:125], v[56:57], off offset:2048
	global_load_dwordx4 v[126:129], v[56:57], off offset:3072
	global_load_dwordx4 v[130:133], v[58:59], off
	global_load_dwordx4 v[134:137], v[58:59], off offset:1024
	global_load_dwordx4 v[138:141], v[58:59], off offset:2048
	global_load_dwordx4 v[142:145], v[58:59], off offset:3072
	s_add_i32 s1, s2, 4
	s_min_i32 s1, s1, s18
	s_lshl_b32 s10, s1, 1
	s_and_b32 s10, s10, -4
	s_add_i32 s10, s73, s10
	v_mov_b32_e32 v55, s10
	ds_read_b32 v54, v55
	s_and_b32 s10, s17, 0xffff
	s_lshl_b32 s10, s10, 5
	s_or_b32 s11, s10, 31
	s_cmp_le_u32 s11, s97
	s_cselect_b32 s22, 1, 0
	s_bfe_u32 s12, s17, 0x40010
	s_lshr_b32 s13, s17, 20
	s_waitcnt vmcnt(24)
	s_cmp_eq_u32 s12, 0
	s_cbranch_scc1 .Lsel_skip_Ba
	v_and_b32_e32 v14, s12, v225
	v_cmp_eq_u32_e32 vcc, 0, v14
	s_cmp_eq_u32 s22, 0
	s_cbranch_scc1 .Lsel_slow_Ba
	v_cndmask_b32_e32 v10, 0, v249, vcc
	v_cndmask_b32_e32 v11, 0, v249, vcc
	v_cndmask_b32_e32 v12, 0, v249, vcc
	v_cndmask_b32_e32 v13, 0, v249, vcc
	s_nop 1
	v_mfma_f32_16x16x32_bf16 v[2:5], v[146:149], v[102:105], v[10:13]
	v_mfma_f32_16x16x32_bf16 v[6:9], v[154:157], v[102:105], v[10:13]
.Lsel_qk2_Ba:
	v_mfma_f32_16x16x32_bf16 v[2:5], v[150:153], v[98:101], v[2:5]
	v_mfma_f32_16x16x32_bf16 v[6:9], v[158:161], v[98:101], v[6:9]
	s_nop 6
	v_max3_f32 v14, v2, v3, v4
	v_max3_f32 v14, v14, v5, v6
	v_max3_f32 v14, v14, v7, v8
	v_max_f32_e32 v14, v14, v9
	v_mov_b32_e32 v16, v14
	s_nop 1
	v_permlane16_swap_b32_e32 v14, v16
	v_max_f32_e32 v14, v14, v16
	v_mov_b32_e32 v16, v14
	s_nop 1
	v_permlane32_swap_b32_e32 v14, v16
	v_max_f32_e32 v14, v14, v16
	v_cmp_gt_f32_e32 vcc, v14, v94
	s_cbranch_vccnz .Lsel_upd_Ba

; __device__ __forceinline__ float xq_max(float v) { const auto r = __builtin_amdgcn_permlane16_swap(__float_as_uint(v), __float_as_uint(v), false, false); return xhalf_max(fmaxf(__uint_as_float(r[0]), __uint_as_float(r[1]))); }
; __device__ __forceinline__ void flash16_compute(bool domask, const bf16x8 (&kf)[4], const bf16x8 (&vf)[4], const bf16x8 (&q)[2], int x0, unsigned span, float& m, float& l, f32x4v (&O)[4]) {
;     ...
;     float mx = fmaxf(fmaxf(fmaxf(sc[0], sc[1]), fmaxf(sc[2], sc[3])), fmaxf(fmaxf(sc[4], sc[5]), fmaxf(sc[6], sc[7])));
;     mx = xq_max(mx);
;     const bool upd = mx > m + SM_THR;
;     if (__ballot(upd) != 0ull) {
.Lsel_qk2_Bb:
	v_mfma_f32_16x16x32_bf16 v[2:5], v[150:153], v[106:109], v[2:5]
	v_mfma_f32_16x16x32_bf16 v[6:9], v[158:161], v[106:109], v[6:9]
	s_nop 6
	v_max3_f32 v14, v2, v3, v4
	v_max3_f32 v14, v14, v5, v6
	v_max3_f32 v14, v14, v7, v8
	v_max_f32_e32 v14, v14, v9
	v_mov_b32_e32 v16, v14
	s_nop 1
	v_permlane16_swap_b32_e32 v14, v16
	v_max_f32_e32 v14, v14, v16
	v_mov_b32_e32 v16, v14
	s_nop 1
	v_permlane32_swap_b32_e32 v14, v16
	v_max_f32_e32 v14, v14, v16
	v_cmp_gt_f32_e32 vcc, v14, v95
	s_cbranch_vccnz .Lsel_upd_Bb

; __device__ __forceinline__ f32x4v mfma16(bf16x8 a, bf16x8 b, f32x4v c) { return __builtin_amdgcn_mfma_f32_16x16x32_bf16(a, b, c, 0, 0, 0); }
; __device__ __forceinline__ float xq_max(float v) { const auto r = __builtin_amdgcn_permlane16_swap(__float_as_uint(v), __float_as_uint(v), false, false); return xhalf_max(fmaxf(__uint_as_float(r[0]), __uint_as_float(r[1]))); }
; #define F16_LOAD(S, KF, VF, E) do { const int sn_ = ((S) < nsteps) ? (S) : nsteps - 1; E = flash16_entry(sn_, list); const size_t go_ = (size_t)(E & 0xffffu) * 256; \
;         flash16_load(kb + go_, vb + go_, KF, VF); } while (0)
; __device__ __forceinline__ void flash16_compute(bool domask, const bf16x8 (&kf)[4], const bf16x8 (&vf)[4], const bf16x8 (&q)[2], int x0, unsigned span, float& m, float& l, f32x4v (&O)[4]) {
;     f32x4v s0 = {0.f, 0.f, 0.f, 0.f}, s1 = {0.f, 0.f, 0.f, 0.f};
;     __builtin_amdgcn_s_setprio(1);
;     s0 = mfma16(kf[0], q[0], s0); s1 = mfma16(kf[2], q[0], s1);
;     s0 = mfma16(kf[1], q[1], s0); s1 = mfma16(kf[3], q[1], s1);
;     __builtin_amdgcn_s_setprio(0);
;     float sc[8] = {s0[0], s0[1], s0[2], s0[3], s1[0], s1[1], s1[2], s1[3]};
;     if (domask) {
; #pragma unroll
;         for (int j = 0; j < 8; ++j) sc[j] = ((unsigned)(x0 + j) <= span) ? sc[j] : -1e30f;
;     }
;     float mx = fmaxf(fmaxf(fmaxf(sc[0], sc[1]), fmaxf(sc[2], sc[3])), fmaxf(fmaxf(sc[4], sc[5]), fmaxf(sc[6], sc[7])));
;     mx = xq_max(mx);
; __device__ __forceinline__ void flash16_run(const bf16x8* kb, const bf16x8* vb, const bf16x8 (&qa)[2], const bf16x8 (&qb)[2], int nsteps, const LAS unsigned* list, int tq, int t0, int qi4, int fq, ...
;     ...
;     F16_LOAD(0, kA, vA, eA); F16_LOAD(1, kB, vB, eB);
; #pragma unroll 1
;     for (int s = 0; s < nsteps; s += 3) {
;         F16_LOAD(s + 2, kC, vC, eC); F16_COMP(kA, vA, eA); if (s + 1 >= nsteps) break;
;         F16_LOAD(s + 3, kA, vA, eA); F16_COMP(kB, vB, eB); if (s + 2 >= nsteps) break;
;         F16_LOAD(s + 4, kB, vB, eB); F16_COMP(kC, vC, eC);
.Lsel_step_C:
	s_add_i32 s1, s2, 3
	s_min_i32 s1, s1, s18
	s_waitcnt lgkmcnt(0)
	v_readfirstlane_b32 s0, v54
	s_and_b32 s5, s1, 1
	s_lshl_b32 s6, s0, 1
	s_and_b32 s6, s6, 0x1fffe
	s_or_b32 s6, s6, s5
	s_and_b32 s0, s0, 0xffff0000
	s_or_b32 s17, s0, s6
	s_lshl_b32 s6, s6, 12
	v_lshl_add_u64 v[56:57], v[230:231], 0, s[6:7]
	v_lshl_add_u64 v[58:59], v[234:235], 0, s[6:7]
	global_load_dwordx4 v[146:149], v[56:57], off
	global_load_dwordx4 v[150:153], v[56:57], off offset:1024
	global_load_dwordx4 v[154:157], v[56:57], off offset:2048
	global_load_dwordx4 v[158:161], v[56:57], off offset:3072
	global_load_dwordx4 v[162:165], v[58:59], off
	global_load_dwordx4 v[166:169], v[58:59], off offset:1024
	global_load_dwordx4 v[170:173], v[58:59], off offset:2048
	global_load_dwordx4 v[174:177], v[58:59], off offset:3072
	s_add_i32 s1, s2, 4
	s_min_i32 s1, s1, s18
	s_lshl_b32 s10, s1, 1
	s_and_b32 s10, s10, -4
	s_add_i32 s10, s73, s10
	v_mov_b32_e32 v55, s10
	ds_read_b32 v54, v55
	s_and_b32 s10, s19, 0xffff
	s_lshl_b32 s10, s10, 5
	s_or_b32 s11, s10, 31
	s_cmp_le_u32 s11, s97
	s_cselect_b32 s22, 1, 0
	s_bfe_u32 s12, s19, 0x40010
	s_lshr_b32 s13, s19, 20
	s_waitcnt vmcnt(24)
	s_cmp_eq_u32 s12, 0
	s_cbranch_scc1 .Lsel_skip_Ca
	v_and_b32_e32 v14, s12, v225
	v_cmp_eq_u32_e32 vcc, 0, v14
	s_cmp_eq_u32 s22, 0
	s_cbranch_scc1 .Lsel_slow_Ca
	v_cndmask_b32_e32 v10, 0, v249, vcc
	v_cndmask_b32_e32 v11, 0, v249, vcc
	v_cndmask_b32_e32 v12, 0, v249, vcc
	v_cndmask_b32_e32 v13, 0, v249, vcc
	s_nop 1
	v_mfma_f32_16x16x32_bf16 v[2:5], v[178:181], v[102:105], v[10:13]
	v_mfma_f32_16x16x32_bf16 v[6:9], v[186:189], v[102:105], v[10:13]
.Lsel_qk2_Ca:
	v_mfma_f32_16x16x32_bf16 v[2:5], v[182:185], v[98:101], v[2:5]
	v_mfma_f32_16x16x32_bf16 v[6:9], v[190:193], v[98:101], v[6:9]
	s_nop 6
	v_max3_f32 v14, v2, v3, v4
	v_max3_f32 v14, v14, v5, v6
	v_max3_f32 v14, v14, v7, v8
	v_max_f32_e32 v14, v14, v9
	v_mov_b32_e32 v16, v14
	s_nop 1
	v_permlane16_swap_b32_e32 v14, v16
	v_max_f32_e32 v14, v14, v16
	v_mov_b32_e32 v16, v14
	s_nop 1
	v_permlane32_swap_b32_e32 v14, v16
	v_max_f32_e32 v14, v14, v16
	v_cmp_gt_f32_e32 vcc, v14, v94
	s_cbranch_vccnz .Lsel_upd_Ca

; __device__ __forceinline__ float ex2(float x) { return __builtin_amdgcn_exp2f(x); }
; __device__ __forceinline__ bf16x8 pack_p(const float* p) { u32x4 w; w.x = cvt_pk_bf16(p[0], p[1]); w.y = cvt_pk_bf16(p[2], p[3]); w.z = cvt_pk_bf16(p[4], p[5]); w.w = cvt_pk_bf16(p[6], p[7]); return __builtin_bit_cast(bf16x8, w); }
; __device__ __forceinline__ f32x4v mfma16(bf16x8 a, bf16x8 b, f32x4v c) { return __builtin_amdgcn_mfma_f32_16x16x32_bf16(a, b, c, 0, 0, 0); }
; __device__ __forceinline__ float xq_max(float v) { const auto r = __builtin_amdgcn_permlane16_swap(__float_as_uint(v), __float_as_uint(v), false, false); return xhalf_max(fmaxf(__uint_as_float(r[0]), __uint_as_float(r[1]))); }
; __device__ __forceinline__ void flash16_compute(bool domask, const bf16x8 (&kf)[4], const bf16x8 (&vf)[4], const bf16x8 (&q)[2], int x0, unsigned span, float& m, float& l, f32x4v (&O)[4]) {
;     ...
;     float mx = fmaxf(fmaxf(fmaxf(sc[0], sc[1]), fmaxf(sc[2], sc[3])), fmaxf(fmaxf(sc[4], sc[5]), fmaxf(sc[6], sc[7])));
;     mx = xq_max(mx);
;     const bool upd = mx > m + SM_THR;
;     if (__ballot(upd) != 0ull) {
;         const float mn = upd ? mx : m, alpha = ex2(m - mn); l *= alpha;
; #pragma unroll
;         for (int dt = 0; dt < 4; ++dt) O[dt] = O[dt] * alpha;
;         m = mn;
;     }
;     const float msub = (m < -1e29f) ? 0.f : m;
;     float p[8], ps = 0.f;
; #pragma unroll
;     for (int j = 0; j < 8; ++j) { p[j] = ex2(sc[j] - msub); ps += p[j]; }
;     l += ps;
;     const bf16x8 pb = pack_p(p);
;     __builtin_amdgcn_s_setprio(1);
; #pragma unroll
;     for (int dt = 0; dt < 4; ++dt) O[dt] = mfma16(vf[dt], pb, O[dt]);
;     __builtin_amdgcn_s_setprio(0);
; }
; __device__ __forceinline__ void flash16_run(const bf16x8* kb, const bf16x8* vb, const bf16x8 (&qa)[2], const bf16x8 (&qb)[2], int nsteps, const LAS unsigned* list, int tq, int t0, int qi4, int fq, ...
;     ...
; #pragma unroll 1
;     for (int s = 0; s < nsteps; s += 3) {
;         F16_LOAD(s + 2, kC, vC, eC); F16_COMP(kA, vA, eA); if (s + 1 >= nsteps) break;
;         F16_LOAD(s + 3, kA, vA, eA); F16_COMP(kB, vB, eB); if (s + 2 >= nsteps) break;
;         F16_LOAD(s + 4, kB, vB, eB); F16_COMP(kC, vC, eC);
.Lsel_qk2_Cb:
	v_mfma_f32_16x16x32_bf16 v[2:5], v[182:185], v[106:109], v[2:5]
	v_mfma_f32_16x16x32_bf16 v[6:9], v[190:193], v[106:109], v[6:9]
	s_nop 6
	v_max3_f32 v14, v2, v3, v4
	v_max3_f32 v14, v14, v5, v6
	v_max3_f32 v14, v14, v7, v8
	v_max_f32_e32 v14, v14, v9
	v_mov_b32_e32 v16, v14
	s_nop 1
	v_permlane16_swap_b32_e32 v14, v16
	v_max_f32_e32 v14, v14, v16
	v_mov_b32_e32 v16, v14
	s_nop 1
	v_permlane32_swap_b32_e32 v14, v16
	v_max_f32_e32 v14, v14, v16
	v_cmp_gt_f32_e32 vcc, v14, v95
	s_cbranch_vccnz .Lsel_upd_Cb
.Lsel_noupd_Cb:
	v_sub_f32_e32 v2, v2, v241
	v_sub_f32_e32 v3, v3, v241
	v_sub_f32_e32 v4, v4, v241
	v_sub_f32_e32 v5, v5, v241
	v_sub_f32_e32 v6, v6, v241
	v_sub_f32_e32 v7, v7, v241
	v_sub_f32_e32 v8, v8, v241
	v_sub_f32_e32 v9, v9, v241
	v_exp_f32_e32 v2, v2
	v_exp_f32_e32 v3, v3
	v_exp_f32_e32 v4, v4
	v_exp_f32_e32 v5, v5
	v_exp_f32_e32 v6, v6
	v_exp_f32_e32 v7, v7
	v_exp_f32_e32 v8, v8
	v_exp_f32_e32 v9, v9
	v_cvt_pk_bf16_f32 v50, v2, v3
	v_cvt_pk_bf16_f32 v51, v4, v5
	v_cvt_pk_bf16_f32 v52, v6, v7
	v_cvt_pk_bf16_f32 v53, v8, v9
	v_add_f32_e32 v14, v2, v3
	v_add_f32_e32 v14, v14, v4
	v_add_f32_e32 v14, v14, v5
	v_add_f32_e32 v14, v14, v6
	v_add_f32_e32 v14, v14, v7
	v_add_f32_e32 v14, v14, v8
	v_add_f32_e32 v14, v14, v9
	v_add_f32_e32 v239, v239, v14
	v_mfma_f32_16x16x32_bf16 v[18:21], v[194:197], v[50:53], v[18:21]
	v_mfma_f32_16x16x32_bf16 v[22:25], v[198:201], v[50:53], v[22:25]
	v_mfma_f32_16x16x32_bf16 v[26:29], v[202:205], v[50:53], v[26:29]
	v_mfma_f32_16x16x32_bf16 v[30:33], v[206:209], v[50:53], v[30:33]
.Lsel_skip_Cb:
	s_add_i32 s2, s2, 1
	s_cmp_ge_u32 s2, s3
	s_cbranch_scc1 .Lsel_done
.Lsel_step_D:
	s_add_i32 s1, s2, 3
	s_min_i32 s1, s1, s18
	s_waitcnt lgkmcnt(0)
	v_readfirstlane_b32 s0, v54
	s_and_b32 s5, s1, 1
	s_lshl_b32 s6, s0, 1
	s_and_b32 s6, s6, 0x1fffe
	s_or_b32 s6, s6, s5
	s_and_b32 s0, s0, 0xffff0000
	s_or_b32 s19, s0, s6
	s_lshl_b32 s6, s6, 12
	v_lshl_add_u64 v[56:57], v[230:231], 0, s[6:7]
	v_lshl_add_u64 v[58:59], v[234:235], 0, s[6:7]
	global_load_dwordx4 v[178:181], v[56:57], off
	global_load_dwordx4 v[182:185], v[56:57], off offset:1024
	global_load_dwordx4 v[186:189], v[56:57], off offset:2048
	global_load_dwordx4 v[190:193], v[56:57], off offset:3072
	global_load_dwordx4 v[194:197], v[58:59], off
	global_load_dwordx4 v[198:201], v[58:59], off offset:1024
	global_load_dwordx4 v[202:205], v[58:59], off offset:2048
	global_load_dwordx4 v[206:209], v[58:59], off offset:3072
	s_add_i32 s1, s2, 4
	s_min_i32 s1, s1, s18
	s_lshl_b32 s10, s1, 1
	s_and_b32 s10, s10, -4
	s_add_i32 s10, s73, s10
	v_mov_b32_e32 v55, s10
	ds_read_b32 v54, v55
	s_and_b32 s10, s4, 0xffff
	s_lshl_b32 s10, s10, 5
	s_or_b32 s11, s10, 31
	s_cmp_le_u32 s11, s97
	s_cselect_b32 s22, 1, 0
	s_bfe_u32 s12, s4, 0x40010
	s_lshr_b32 s13, s4, 20
	s_waitcnt vmcnt(24)
	s_cmp_eq_u32 s12, 0
	s_cbranch_scc1 .Lsel_skip_Da
	v_and_b32_e32 v14, s12, v225
	v_cmp_eq_u32_e32 vcc, 0, v14
	s_cmp_eq_u32 s22, 0
	s_cbranch_scc1 .Lsel_slow_Da
	v_cndmask_b32_e32 v10, 0, v249, vcc
	v_cndmask_b32_e32 v11, 0, v249, vcc
	v_cndmask_b32_e32 v12, 0, v249, vcc
	v_cndmask_b32_e32 v13, 0, v249, vcc
	s_nop 1
	v_mfma_f32_16x16x32_bf16 v[2:5], v[62:65], v[102:105], v[10:13]
	v_mfma_f32_16x16x32_bf16 v[6:9], v[70:73], v[102:105], v[10:13]
.Lsel_qk2_Da:
	v_mfma_f32_16x16x32_bf16 v[2:5], v[66:69], v[98:101], v[2:5]
	v_mfma_f32_16x16x32_bf16 v[6:9], v[74:77], v[98:101], v[6:9]
	s_nop 6
	v_max3_f32 v14, v2, v3, v4
	v_max3_f32 v14, v14, v5, v6
	v_max3_f32 v14, v14, v7, v8
	v_max_f32_e32 v14, v14, v9
	v_mov_b32_e32 v16, v14
	s_nop 1
	v_permlane16_swap_b32_e32 v14, v16
	v_max_f32_e32 v14, v14, v16
	v_mov_b32_e32 v16, v14
	s_nop 1
	v_permlane32_swap_b32_e32 v14, v16
	v_max_f32_e32 v14, v14, v16
	v_cmp_gt_f32_e32 vcc, v14, v94
	s_cbranch_vccnz .Lsel_upd_Da
.Lsel_noupd_Da:
	v_sub_f32_e32 v2, v2, v240
	v_sub_f32_e32 v3, v3, v240
	v_sub_f32_e32 v4, v4, v240
	v_sub_f32_e32 v5, v5, v240
	v_sub_f32_e32 v6, v6, v240
	v_sub_f32_e32 v7, v7, v240
	v_sub_f32_e32 v8, v8, v240
	v_sub_f32_e32 v9, v9, v240
	v_exp_f32_e32 v2, v2
	v_exp_f32_e32 v3, v3
	v_exp_f32_e32 v4, v4
	v_exp_f32_e32 v5, v5
	v_exp_f32_e32 v6, v6
	v_exp_f32_e32 v7, v7
	v_exp_f32_e32 v8, v8
	v_exp_f32_e32 v9, v9
	v_cvt_pk_bf16_f32 v50, v2, v3
	v_cvt_pk_bf16_f32 v51, v4, v5
	v_cvt_pk_bf16_f32 v52, v6, v7
	v_cvt_pk_bf16_f32 v53, v8, v9
	v_add_f32_e32 v14, v2, v3
	v_add_f32_e32 v14, v14, v4
	v_add_f32_e32 v14, v14, v5
	v_add_f32_e32 v14, v14, v6
	v_add_f32_e32 v14, v14, v7
	v_add_f32_e32 v14, v14, v8
	v_add_f32_e32 v14, v14, v9
	v_add_f32_e32 v238, v238, v14
	v_mfma_f32_16x16x32_bf16 v[34:37], v[78:81], v[50:53], v[34:37]
	v_mfma_f32_16x16x32_bf16 v[38:41], v[82:85], v[50:53], v[38:41]
	v_mfma_f32_16x16x32_bf16 v[42:45], v[86:89], v[50:53], v[42:45]
	v_mfma_f32_16x16x32_bf16 v[46:49], v[90:93], v[50:53], v[46:49]
.Lsel_skip_Da:
	s_cmp_eq_u32 s13, 0
	s_cbranch_scc1 .Lsel_skip_Db
	v_and_b32_e32 v14, s13, v225
	v_cmp_eq_u32_e32 vcc, 0, v14
	s_cmp_eq_u32 s22, 0
	s_cbranch_scc1 .Lsel_slow_Db
	v_cndmask_b32_e32 v10, 0, v249, vcc
	v_cndmask_b32_e32 v11, 0, v249, vcc
	v_cndmask_b32_e32 v12, 0, v249, vcc
	v_cndmask_b32_e32 v13, 0, v249, vcc
	s_nop 1
	v_mfma_f32_16x16x32_bf16 v[2:5], v[62:65], v[110:113], v[10:13]
	v_mfma_f32_16x16x32_bf16 v[6:9], v[70:73], v[110:113], v[10:13]
.Lsel_qk2_Db:
	v_mfma_f32_16x16x32_bf16 v[2:5], v[66:69], v[106:109], v[2:5]
	v_mfma_f32_16x16x32_bf16 v[6:9], v[74:77], v[106:109], v[6:9]
	s_nop 6
	v_max3_f32 v14, v2, v3, v4
	v_max3_f32 v14, v14, v5, v6
	v_max3_f32 v14, v14, v7, v8
	v_max_f32_e32 v14, v14, v9
	v_mov_b32_e32 v16, v14
	s_nop 1
	v_permlane16_swap_b32_e32 v14, v16
	v_max_f32_e32 v14, v14, v16
	v_mov_b32_e32 v16, v14
	s_nop 1
	v_permlane32_swap_b32_e32 v14, v16
	v_max_f32_e32 v14, v14, v16
	v_cmp_gt_f32_e32 vcc, v14, v95
	s_cbranch_vccnz .Lsel_upd_Db
.Lsel_noupd_Db:
	v_sub_f32_e32 v2, v2, v241
	v_sub_f32_e32 v3, v3, v241
	v_sub_f32_e32 v4, v4, v241
	v_sub_f32_e32 v5, v5, v241
	v_sub_f32_e32 v6, v6, v241
	v_sub_f32_e32 v7, v7, v241
	v_sub_f32_e32 v8, v8, v241
	v_sub_f32_e32 v9, v9, v241
	v_exp_f32_e32 v2, v2
	v_exp_f32_e32 v3, v3
	v_exp_f32_e32 v4, v4
	v_exp_f32_e32 v5, v5
	v_exp_f32_e32 v6, v6
	v_exp_f32_e32 v7, v7
	v_exp_f32_e32 v8, v8
	v_exp_f32_e32 v9, v9
	v_cvt_pk_bf16_f32 v50, v2, v3
	v_cvt_pk_bf16_f32 v51, v4, v5
	v_cvt_pk_bf16_f32 v52, v6, v7
	v_cvt_pk_bf16_f32 v53, v8, v9
	v_add_f32_e32 v14, v2, v3
	v_add_f32_e32 v14, v14, v4
	v_add_f32_e32 v14, v14, v5
	v_add_f32_e32 v14, v14, v6
	v_add_f32_e32 v14, v14, v7
	v_add_f32_e32 v14, v14, v8
	v_add_f32_e32 v14, v14, v9
	v_add_f32_e32 v239, v239, v14
	v_mfma_f32_16x16x32_bf16 v[18:21], v[78:81], v[50:53], v[18:21]
	v_mfma_f32_16x16x32_bf16 v[22:25], v[82:85], v[50:53], v[22:25]
	v_mfma_f32_16x16x32_bf16 v[26:29], v[86:89], v[50:53], v[26:29]
	v_mfma_f32_16x16x32_bf16 v[30:33], v[90:93], v[50:53], v[30:33]

; __device__ __forceinline__ float ex2(float x) { return __builtin_amdgcn_exp2f(x); }
; __device__ __forceinline__ void flash16_compute(bool domask, const bf16x8 (&kf)[4], const bf16x8 (&vf)[4], const bf16x8 (&q)[2], int x0, unsigned span, float& m, float& l, f32x4v (&O)[4]) {
;     ...
;     const bool upd = mx > m + SM_THR;
;     if (__ballot(upd) != 0ull) {
;         const float mn = upd ? mx : m, alpha = ex2(m - mn); l *= alpha;
; #pragma unroll
;         for (int dt = 0; dt < 4; ++dt) O[dt] = O[dt] * alpha;
;         m = mn;
;     }
;     const float msub = (m < -1e29f) ? 0.f : m;
.Lsel_upd_Aa:
	s_nop 1
	v_cndmask_b32_e32 v16, v236, v14, vcc
	v_sub_f32_e32 v17, v236, v16
	v_exp_f32_e32 v17, v17
	v_mov_b32_e32 v236, v16
	v_add_f32_e32 v94, 0x41000000, v16
	v_mul_f32_e32 v238, v238, v17
	v_mul_f32_e32 v34, v34, v17
	v_mul_f32_e32 v35, v35, v17
	v_mul_f32_e32 v36, v36, v17
	v_mul_f32_e32 v37, v37, v17
	v_mul_f32_e32 v38, v38, v17
	v_mul_f32_e32 v39, v39, v17
	v_mul_f32_e32 v40, v40, v17
	v_mul_f32_e32 v41, v41, v17
	v_mul_f32_e32 v42, v42, v17
	v_mul_f32_e32 v43, v43, v17
	v_mul_f32_e32 v44, v44, v17
	v_mul_f32_e32 v45, v45, v17
	v_mul_f32_e32 v46, v46, v17
	v_mul_f32_e32 v47, v47, v17
	v_mul_f32_e32 v48, v48, v17
	v_mul_f32_e32 v49, v49, v17
	v_cmp_ngt_f32_e32 vcc, s66, v16
	s_nop 1
	v_cndmask_b32_e32 v240, 0, v16, vcc
	s_branch .Lsel_noupd_Aa

; __device__ __forceinline__ float ex2(float x) { return __builtin_amdgcn_exp2f(x); }
; __device__ __forceinline__ void flash16_compute(bool domask, const bf16x8 (&kf)[4], const bf16x8 (&vf)[4], const bf16x8 (&q)[2], int x0, unsigned span, float& m, float& l, f32x4v (&O)[4]) {
;     ...
;     const bool upd = mx > m + SM_THR;
;     if (__ballot(upd) != 0ull) {
;         const float mn = upd ? mx : m, alpha = ex2(m - mn); l *= alpha;
; #pragma unroll
;         for (int dt = 0; dt < 4; ++dt) O[dt] = O[dt] * alpha;
;         m = mn;
;     }
;     const float msub = (m < -1e29f) ? 0.f : m;
.Lsel_upd_Ab:
	s_nop 1
	v_cndmask_b32_e32 v16, v237, v14, vcc
	v_sub_f32_e32 v17, v237, v16
	v_exp_f32_e32 v17, v17
	v_mov_b32_e32 v237, v16
	v_add_f32_e32 v95, 0x41000000, v16
	v_mul_f32_e32 v239, v239, v17
	v_mul_f32_e32 v18, v18, v17
	v_mul_f32_e32 v19, v19, v17
	v_mul_f32_e32 v20, v20, v17
	v_mul_f32_e32 v21, v21, v17
	v_mul_f32_e32 v22, v22, v17
	v_mul_f32_e32 v23, v23, v17
	v_mul_f32_e32 v24, v24, v17
	v_mul_f32_e32 v25, v25, v17
	v_mul_f32_e32 v26, v26, v17
	v_mul_f32_e32 v27, v27, v17
	v_mul_f32_e32 v28, v28, v17
	v_mul_f32_e32 v29, v29, v17
	v_mul_f32_e32 v30, v30, v17
	v_mul_f32_e32 v31, v31, v17
	v_mul_f32_e32 v32, v32, v17
	v_mul_f32_e32 v33, v33, v17
	v_cmp_ngt_f32_e32 vcc, s66, v16
	s_nop 1
	v_cndmask_b32_e32 v241, 0, v16, vcc
	s_branch .Lsel_noupd_Ab

; __device__ __forceinline__ f32x4v mfma16(bf16x8 a, bf16x8 b, f32x4v c) { return __builtin_amdgcn_mfma_f32_16x16x32_bf16(a, b, c, 0, 0, 0); }
; __device__ __forceinline__ void flash16_compute(bool domask, const bf16x8 (&kf)[4], const bf16x8 (&vf)[4], const bf16x8 (&q)[2], int x0, unsigned span, float& m, float& l, f32x4v (&O)[4]) {
;     f32x4v s0 = {0.f, 0.f, 0.f, 0.f}, s1 = {0.f, 0.f, 0.f, 0.f};
;     __builtin_amdgcn_s_setprio(1);
;     s0 = mfma16(kf[0], q[0], s0); s1 = mfma16(kf[2], q[0], s1);
;     s0 = mfma16(kf[1], q[1], s0); s1 = mfma16(kf[3], q[1], s1);
;     __builtin_amdgcn_s_setprio(0);
;     float sc[8] = {s0[0], s0[1], s0[2], s0[3], s1[0], s1[1], s1[2], s1[3]};
;     if (domask) {
; #pragma unroll
;         for (int j = 0; j < 8; ++j) sc[j] = ((unsigned)(x0 + j) <= span) ? sc[j] : -1e30f;
.Lsel_slow_Da:
	v_subrev_u32_e32 v16, s10, v211
	s_nop 0
	v_cndmask_b32_e64 v16, v16, -1, vcc
	v_cmp_lt_i32_e32 vcc, -1, v16
	v_max_i32_e32 v17, 0, v16
	s_nop 0
	v_cndmask_b32_e32 v16, 64, v232, vcc
	v_cmp_le_u32_e32 vcc, v16, v17
	s_nop 1
	v_cndmask_b32_e32 v2, v249, v1, vcc
	v_or_b32_e32 v15, 1, v16
	v_cmp_le_u32_e32 vcc, v15, v17
	s_nop 1
	v_cndmask_b32_e32 v3, v249, v1, vcc
	v_or_b32_e32 v15, 2, v16
	v_cmp_le_u32_e32 vcc, v15, v17
	s_nop 1
	v_cndmask_b32_e32 v4, v249, v1, vcc
	v_or_b32_e32 v15, 3, v16
	v_cmp_le_u32_e32 vcc, v15, v17
	s_nop 1
	v_cndmask_b32_e32 v5, v249, v1, vcc
	v_or_b32_e32 v15, 4, v16
	v_cmp_le_u32_e32 vcc, v15, v17
	s_nop 1
	v_cndmask_b32_e32 v6, v249, v1, vcc
	v_or_b32_e32 v15, 5, v16
	v_cmp_le_u32_e32 vcc, v15, v17
	s_nop 1
	v_cndmask_b32_e32 v7, v249, v1, vcc
	v_or_b32_e32 v15, 6, v16
	v_cmp_le_u32_e32 vcc, v15, v17
	s_nop 1
	v_cndmask_b32_e32 v8, v249, v1, vcc
	v_or_b32_e32 v15, 7, v16
	v_cmp_le_u32_e32 vcc, v15, v17
	s_nop 1
	v_cndmask_b32_e32 v9, v249, v1, vcc
	s_nop 1
	v_mfma_f32_16x16x32_bf16 v[2:5], v[62:65], v[102:105], v[2:5]
	v_mfma_f32_16x16x32_bf16 v[6:9], v[70:73], v[102:105], v[6:9]
	s_branch .Lsel_qk2_Da

; __device__ __forceinline__ f32x4v mfma16(bf16x8 a, bf16x8 b, f32x4v c) { return __builtin_amdgcn_mfma_f32_16x16x32_bf16(a, b, c, 0, 0, 0); }
; __device__ __forceinline__ void flash16_compute(bool domask, const bf16x8 (&kf)[4], const bf16x8 (&vf)[4], const bf16x8 (&q)[2], int x0, unsigned span, float& m, float& l, f32x4v (&O)[4]) {
;     f32x4v s0 = {0.f, 0.f, 0.f, 0.f}, s1 = {0.f, 0.f, 0.f, 0.f};
;     __builtin_amdgcn_s_setprio(1);
;     s0 = mfma16(kf[0], q[0], s0); s1 = mfma16(kf[2], q[0], s1);
;     s0 = mfma16(kf[1], q[1], s0); s1 = mfma16(kf[3], q[1], s1);
;     __builtin_amdgcn_s_setprio(0);
;     float sc[8] = {s0[0], s0[1], s0[2], s0[3], s1[0], s1[1], s1[2], s1[3]};
;     if (domask) {
; #pragma unroll
;         for (int j = 0; j < 8; ++j) sc[j] = ((unsigned)(x0 + j) <= span) ? sc[j] : -1e30f;
.Lsel_slow_Db:
	v_subrev_u32_e32 v16, s10, v227
	s_nop 0
	v_cndmask_b32_e64 v16, v16, -1, vcc
	v_cmp_lt_i32_e32 vcc, -1, v16
	v_max_i32_e32 v17, 0, v16
	s_nop 0
	v_cndmask_b32_e32 v16, 64, v232, vcc
	v_cmp_le_u32_e32 vcc, v16, v17
	s_nop 1
	v_cndmask_b32_e32 v2, v249, v1, vcc
	v_or_b32_e32 v15, 1, v16
	v_cmp_le_u32_e32 vcc, v15, v17
	s_nop 1
	v_cndmask_b32_e32 v3, v249, v1, vcc
	v_or_b32_e32 v15, 2, v16
	v_cmp_le_u32_e32 vcc, v15, v17
	s_nop 1
	v_cndmask_b32_e32 v4, v249, v1, vcc
	v_or_b32_e32 v15, 3, v16
	v_cmp_le_u32_e32 vcc, v15, v17
	s_nop 1
	v_cndmask_b32_e32 v5, v249, v1, vcc
	v_or_b32_e32 v15, 4, v16
	v_cmp_le_u32_e32 vcc, v15, v17
	s_nop 1
	v_cndmask_b32_e32 v6, v249, v1, vcc
	v_or_b32_e32 v15, 5, v16
	v_cmp_le_u32_e32 vcc, v15, v17
	s_nop 1
	v_cndmask_b32_e32 v7, v249, v1, vcc
	v_or_b32_e32 v15, 6, v16
	v_cmp_le_u32_e32 vcc, v15, v17
	s_nop 1
	v_cndmask_b32_e32 v8, v249, v1, vcc
	v_or_b32_e32 v15, 7, v16
	v_cmp_le_u32_e32 vcc, v15, v17
	s_nop 1
	v_cndmask_b32_e32 v9, v249, v1, vcc
	s_nop 1
	v_mfma_f32_16x16x32_bf16 v[2:5], v[62:65], v[110:113], v[2:5]
	v_mfma_f32_16x16x32_bf16 v[6:9], v[70:73], v[110:113], v[6:9]
	s_branch .Lsel_qk2_Db

; #define LAS __attribute__((address_space(3)))
; __device__ __forceinline__ float bf1(bf16_t u) { return __uint_as_float(((unsigned)u) << 16); }
; __device__ __forceinline__ float sigm(float x) { return rcpf_(1.f + ex2(-1.44269504f * x)); }
; #define LDS_WAIT() asm volatile("s_waitcnt lgkmcnt(0)" ::: "memory")
; __device__ __forceinline__ float xq_sum(float v) { const auto r = __builtin_amdgcn_permlane16_swap(__float_as_uint(v), __float_as_uint(v), false, false); return xhalf_sum(__uint_as_float(r[0]) + __uint_as_float(r[1])); }
; __device__ __forceinline__ void nsa_tile(const Ctx& C, int b, int g, int t0) {
;     ...
;             gs4[sub] = sigm(bf1(P[tok4 * PP + PC_NG + head4 * 3 + 1]));
;         }
;         float ma = -1e30f, la = 0.f, mb = -1e30f, lb = 0.f; f32x4v Oa[4], Ob[4];
; #pragma unroll
;         for (int dt = 0; dt < 4; ++dt) { Oa[dt] = (f32x4v){0.f, 0.f, 0.f, 0.f}; Ob[dt] = (f32x4v){0.f, 0.f, 0.f, 0.f}; }
;         flash16_run(kb, vb, q16f[0], q16f[1], 2 * nblk, list, tq, t0, qi4, fq, ma, la, Oa, mb, lb, Ob);
;         la = xq_sum(la); lb = xq_sum(lb);
;         const float sca = gs4[0] / fmaxf(la, 1e-30f), scb = gs4[1] / fmaxf(lb, 1e-30f);
; #pragma unroll
;         for (int dt = 0; dt < 4; ++dt)
; #pragma unroll
;             for (int i = 0; i < 4; ++i) { LAS float* op = ostb + ((dt >> 1) * 16 + 4 * (2 * (dt & 1) + (fq >> 1)) + i) * 64 + q16 + 32 * (fq & 1); op[0] += sca * Oa[dt][i]; op[16] += scb * Ob[dt][i]; }
;         LDS_WAIT();
.LBB0_866:
	s_waitcnt vmcnt(1)
	v_lshlrev_b32_e32 v3, 16, v251
	v_mul_f32_e32 v3, 0xbfb8aa3b, v3
	v_mov_b32_e32 v5, v238
	v_exp_f32_e32 v3, v3
	s_nop 0
	v_permlane16_swap_b32_e32 v238, v5
	v_add_f32_e32 v5, v238, v5
	v_mov_b32_e32 v6, v5
	s_nop 1
	v_permlane32_swap_b32_e32 v5, v6
	v_add_f32_e32 v3, 1.0, v3
	v_add_f32_e32 v5, v5, v6
	v_mov_b32_e32 v6, v239
	v_rcp_f32_e32 v3, v3
	s_nop 0
	v_permlane16_swap_b32_e32 v239, v6
	v_add_f32_e32 v6, v239, v6
	v_mov_b32_e32 v7, v6
	s_nop 1
	v_permlane32_swap_b32_e32 v6, v7
	v_max_f32_e32 v5, 0xda24260, v5
	v_add_f32_e32 v6, v6, v7
	v_div_scale_f32 v7, s[0:1], v5, v5, v3
	v_rcp_f32_e32 v8, v7
	s_waitcnt vmcnt(0)
	v_lshlrev_b32_e32 v4, 16, v210
	v_mul_f32_e32 v4, 0xbfb8aa3b, v4
	v_exp_f32_e32 v4, v4
	v_fma_f32 v9, -v7, v8, 1.0
	v_fmac_f32_e32 v8, v9, v8
	v_div_scale_f32 v9, vcc, v3, v5, v3
	v_mul_f32_e32 v10, v9, v8
	v_add_f32_e32 v4, 1.0, v4
	v_fma_f32 v11, -v7, v10, v9
	v_rcp_f32_e32 v4, v4
	v_fmac_f32_e32 v10, v11, v8
	v_fma_f32 v7, -v7, v10, v9
	v_div_fmas_f32 v7, v7, v8, v10
	v_div_fixup_f32 v5, v7, v5, v3
	v_max_f32_e32 v3, 0xda24260, v6
	v_div_scale_f32 v6, s[0:1], v3, v3, v4
	v_rcp_f32_e32 v7, v6
	v_and_b32_e32 v2, 15, v224
	v_lshl_add_u32 v2, v2, 2, s73
	s_max_i32 s1, s97, 0x1ff
	v_fma_f32 v8, -v6, v7, 1.0
	v_fmac_f32_e32 v7, v8, v7
	v_div_scale_f32 v8, vcc, v4, v3, v4
	v_mul_f32_e32 v9, v8, v7
	v_fma_f32 v10, -v6, v9, v8
	v_fmac_f32_e32 v9, v10, v7
	v_fma_f32 v6, -v6, v9, v8
	v_div_fmas_f32 v6, v6, v7, v9
	v_div_fixup_f32 v4, v6, v3, v4
	v_lshlrev_b32_e32 v3, 7, v245
	v_and_b32_e32 v3, 0x80, v3
	v_lshlrev_b32_e32 v6, 10, v244
	v_add3_u32 v6, v2, v3, v6
	v_add_u32_e32 v7, 0x2000, v6
	ds_read2_b32 v[2:3], v7 offset0:64 offset1:80
	s_addk_i32 s1, 0xfe01
	s_lshr_b32 s0, s1, 5
	s_lshr_b32 s4, s97, 5
	s_sub_i32 s2, s4, s0
	s_waitcnt lgkmcnt(0)
	v_fma_f32 v2, v34, v5, v2
	v_fmac_f32_e32 v3, v18, v4
	ds_write2_b32 v7, v2, v3 offset0:64 offset1:80
	ds_read2_b32 v[2:3], v7 offset0:128 offset1:144
	s_mov_b32 s3, 0
	s_cmp_lt_i32 s2, 0
	s_waitcnt lgkmcnt(0)
	v_fma_f32 v2, v35, v5, v2
	v_fmac_f32_e32 v3, v19, v4
	ds_write2_b32 v7, v2, v3 offset0:128 offset1:144
	ds_read2_b32 v[2:3], v7 offset0:192 offset1:208
	s_waitcnt lgkmcnt(0)
	v_fma_f32 v2, v36, v5, v2
	v_fmac_f32_e32 v3, v20, v4
	ds_write2_b32 v7, v2, v3 offset0:192 offset1:208
	v_add_u32_e32 v7, 0x2400, v6
	ds_read2_b32 v[2:3], v7 offset1:16
	s_waitcnt lgkmcnt(0)
	v_fma_f32 v2, v37, v5, v2
	v_fmac_f32_e32 v3, v21, v4
	ds_write2_b32 v7, v2, v3 offset1:16
	v_add_u32_e32 v7, 0x2800, v6
	ds_read2_b32 v[2:3], v7 offset0:64 offset1:80
	s_waitcnt lgkmcnt(0)
	v_fma_f32 v2, v38, v5, v2
	v_fmac_f32_e32 v3, v22, v4
	ds_write2_b32 v7, v2, v3 offset0:64 offset1:80
	ds_read2_b32 v[2:3], v7 offset0:128 offset1:144
	s_waitcnt lgkmcnt(0)
	v_fma_f32 v2, v39, v5, v2
	v_fmac_f32_e32 v3, v23, v4
	ds_write2_b32 v7, v2, v3 offset0:128 offset1:144
	ds_read2_b32 v[2:3], v7 offset0:192 offset1:208
	s_waitcnt lgkmcnt(0)
	v_fma_f32 v2, v40, v5, v2
	v_fmac_f32_e32 v3, v24, v4
	ds_write2_b32 v7, v2, v3 offset0:192 offset1:208
	v_add_u32_e32 v7, 0x2c00, v6
	ds_read2_b32 v[2:3], v7 offset1:16
	s_waitcnt lgkmcnt(0)
	v_fma_f32 v2, v41, v5, v2
	v_fmac_f32_e32 v3, v25, v4
	ds_write2_b32 v7, v2, v3 offset1:16
	v_add_u32_e32 v7, 0x3000, v6
	ds_read2_b32 v[2:3], v7 offset0:64 offset1:80
	s_waitcnt lgkmcnt(0)
	v_fma_f32 v2, v42, v5, v2
	v_fmac_f32_e32 v3, v26, v4
	ds_write2_b32 v7, v2, v3 offset0:64 offset1:80
	ds_read2_b32 v[2:3], v7 offset0:128 offset1:144
	s_waitcnt lgkmcnt(0)
	v_fma_f32 v2, v43, v5, v2
	v_fmac_f32_e32 v3, v27, v4
	ds_write2_b32 v7, v2, v3 offset0:128 offset1:144
	ds_read2_b32 v[2:3], v7 offset0:192 offset1:208
	s_waitcnt lgkmcnt(0)
	v_fma_f32 v2, v44, v5, v2
	v_fmac_f32_e32 v3, v28, v4
	ds_write2_b32 v7, v2, v3 offset0:192 offset1:208
	v_add_u32_e32 v7, 0x3400, v6
	ds_read2_b32 v[2:3], v7 offset1:16
	s_waitcnt lgkmcnt(0)
	v_fma_f32 v2, v45, v5, v2
	v_fmac_f32_e32 v3, v29, v4
	ds_write2_b32 v7, v2, v3 offset1:16
	v_add_u32_e32 v7, 0x3800, v6
	ds_read2_b32 v[2:3], v7 offset0:64 offset1:80
	v_add_u32_e32 v6, 0x3c00, v6
	s_waitcnt lgkmcnt(0)
	v_fma_f32 v2, v46, v5, v2
	v_fmac_f32_e32 v3, v30, v4
	ds_write2_b32 v7, v2, v3 offset0:64 offset1:80
	ds_read2_b32 v[2:3], v7 offset0:128 offset1:144
	s_waitcnt lgkmcnt(0)
	v_fma_f32 v2, v47, v5, v2
	v_fmac_f32_e32 v3, v31, v4
	ds_write2_b32 v7, v2, v3 offset0:128 offset1:144
	ds_read2_b32 v[2:3], v7 offset0:192 offset1:208
	s_waitcnt lgkmcnt(0)
	v_fma_f32 v2, v48, v5, v2
	v_fmac_f32_e32 v3, v32, v4
	ds_write2_b32 v7, v2, v3 offset0:192 offset1:208
	ds_read2_b32 v[2:3], v6 offset1:16
	s_waitcnt lgkmcnt(0)
	v_fma_f32 v2, v49, v5, v2
	v_fmac_f32_e32 v3, v33, v4
	ds_write2_b32 v6, v2, v3 offset1:16
	s_waitcnt lgkmcnt(0)
	s_cbranch_scc1 .LBB0_648
; __device__ __forceinline__ float bf_lo(unsigned u) { return __uint_as_float(u << 16); }
; __device__ __forceinline__ float bf_hi(unsigned u) { return __uint_as_float(u & 0xffff0000u); }
; __device__ __forceinline__ bf16x8 pack_p(const float* p) { u32x4 w; w.x = cvt_pk_bf16(p[0], p[1]); w.y = cvt_pk_bf16(p[2], p[3]); w.z = cvt_pk_bf16(p[4], p[5]); w.w = cvt_pk_bf16(p[6], p[7]); return __builtin_bit_cast(bf16x8, w); }
; __device__ __forceinline__ bf16x8 scale_q(u32x4 v, float s) { u32x4 w; w.x = cvt_pk_bf16(bf_lo(v.x) * s, bf_hi(v.x) * s); w.y = cvt_pk_bf16(bf_lo(v.y) * s, bf_hi(v.y) * s); w.z = cvt_pk_bf16(bf_lo(v.z) * s, bf_hi(v.z) * s); w.w = cvt_pk_bf16(bf_lo(v.w) * s, bf_hi(v.w) * s); return __builtin_bit_cast(bf16x8, w); }
; __device__ __forceinline__ void nsa_tile(const Ctx& C, int b, int g, int t0) {
;     ...
;         bf16x8 qr[4];
;         {
;             const bf16_t* qp = P + tok * PP + PC_Q + head * 64;
; #pragma unroll
;             for (int s = 1; s < 4; ++s) qr[s] = scale_q(*(const u32x4*)(qp + 16 * s + 8 * hi), QS);
;             const u32x4 mv4 = *(const u32x4*)(qp + 8 * hi), pv4 = *(const u32x4*)(qp + 8 * (hi ^ 1));
;             const float* rt = (const float*)(C.ws + WS_ROPE) + tok * 16;
;             const f32x4 ca = *(const f32x4*)rt, cb2 = *(const f32x4*)(rt + 4), sa = *(const f32x4*)(rt + 8), sb = *(const f32x4*)(rt + 12);
;             const float cs[8] = {ca.x, ca.y, ca.z, ca.w, cb2.x, cb2.y, cb2.z, cb2.w}, sn[8] = {sa.x, sa.y, sa.z, sa.w, sb.x, sb.y, sb.z, sb.w};
;             const float mv[8] = {bf_lo(mv4.x), bf_hi(mv4.x), bf_lo(mv4.y), bf_hi(mv4.y), bf_lo(mv4.z), bf_hi(mv4.z), bf_lo(mv4.w), bf_hi(mv4.w)};
;             const float pp[8] = {bf_lo(pv4.x), bf_hi(pv4.x), bf_lo(pv4.y), bf_hi(pv4.y), bf_lo(pv4.z), bf_hi(pv4.z), bf_lo(pv4.w), bf_hi(pv4.w)};
;             const float sg = hi ? 1.f : -1.f; float o[8];
; #pragma unroll
;             for (int e = 0; e < 8; ++e) o[e] = (mv[e] * cs[e] + sg * pp[e] * sn[e]) * QS;
;             qr[0] = pack_p(o);
;         }
	v_xor_b32_e32 v22, 8, v218
	v_lshlrev_b64 v[2:3], 6, v[0:1]
	v_ashrrev_i32_e32 v23, 31, v22
	v_lshl_add_u64 v[14:15], s[78:79], 0, v[2:3]
	v_lshl_add_u64 v[22:23], v[22:23], 1, v[222:223]
	global_load_dwordx4 v[2:5], v[14:15], off offset:16
	global_load_dwordx4 v[6:9], v[14:15], off offset:48
	global_load_dwordx4 v[10:13], v[14:15], off
	s_nop 0
	global_load_dwordx4 v[14:17], v[14:15], off offset:32
	s_nop 0
	global_load_dwordx4 v[18:21], v[220:221], off offset:3072
	v_cmp_gt_u32_e32 vcc, 32, v224
	global_load_dwordx4 v[22:25], v[22:23], off offset:3072
	global_load_dwordx4 v[114:117], v[220:221], off offset:3168
	global_load_dwordx4 v[118:121], v[220:221], off offset:3136
	global_load_dwordx4 v[122:125], v[220:221], off offset:3104
	s_lshl_b64 s[10:11], s[30:31], 21
	s_add_u32 s12, s29, s10
	s_addc_u32 s13, s37, s11
	s_add_u32 s10, s59, s10
	s_addc_u32 s11, s80, s11
	s_and_b32 s5, s1, 0xffffffe0
	s_or_b32 s1, s1, 31
	s_cmp_gt_i32 s1, s97
	v_lshl_add_u64 v[164:165], s[10:11], 0, v[228:229]
	s_cselect_b64 s[10:11], -1, 0
	s_add_i32 s16, s97, 0xfffffe08
	s_cmp_lt_i32 s5, s16
	v_lshl_add_u64 v[162:163], s[12:13], 0, v[228:229]
	s_cselect_b64 s[12:13], -1, 0
	s_or_b64 s[10:11], s[10:11], s[12:13]
	s_and_b64 s[10:11], s[10:11], exec
	s_mov_b32 s1, s7
	s_cselect_b32 s17, 2, 0
	s_lshl_b64 s[10:11], s[0:1], 12
	s_waitcnt vmcnt(6)
	v_mov_b32_e32 v28, v10
	s_waitcnt vmcnt(5)
	v_mov_b32_e32 v29, v14
	s_waitcnt vmcnt(4)
	v_lshlrev_b32_e32 v26, 16, v18
	v_mov_b32_e32 v14, v11
	s_waitcnt vmcnt(3)
	v_lshlrev_b32_e32 v27, 16, v22
	v_cndmask_b32_e64 v27, v27, -v27, vcc
	v_pk_mul_f32 v[26:27], v[28:29], v[26:27]
	s_nop 0
	v_add_f32_e32 v10, v26, v27
	v_mul_f32_e32 v28, 0x3e38aa3b, v10
	v_and_b32_e32 v10, 0xffff0000, v22
	v_and_b32_e32 v26, 0xffff0000, v18
	v_cndmask_b32_e64 v27, v10, -v10, vcc
	v_pk_mul_f32 v[10:11], v[14:15], v[26:27]
	v_mov_b32_e32 v14, v12
	v_add_f32_e32 v10, v10, v11
	v_mul_f32_e32 v10, 0x3e38aa3b, v10
	v_lshlrev_b32_e32 v11, 16, v23
	v_cvt_pk_bf16_f32 v50, v28, v10
	v_lshlrev_b32_e32 v10, 16, v19
	v_cndmask_b32_e64 v11, v11, -v11, vcc
	v_mov_b32_e32 v15, v16
	v_pk_mul_f32 v[10:11], v[14:15], v[10:11]
	v_mov_b32_e32 v16, v13
	v_add_f32_e32 v10, v10, v11
	v_and_b32_e32 v11, 0xffff0000, v23
	v_mul_f32_e32 v12, 0x3e38aa3b, v10
	v_and_b32_e32 v10, 0xffff0000, v19
	v_cndmask_b32_e64 v11, v11, -v11, vcc
	v_pk_mul_f32 v[10:11], v[16:17], v[10:11]
	v_mov_b32_e32 v13, v6
	v_add_f32_e32 v10, v10, v11
	v_mul_f32_e32 v10, 0x3e38aa3b, v10
	v_lshlrev_b32_e32 v11, 16, v24
	v_cvt_pk_bf16_f32 v51, v12, v10
	v_lshlrev_b32_e32 v10, 16, v20
	v_cndmask_b32_e64 v11, v11, -v11, vcc
	v_mov_b32_e32 v12, v2
	v_pk_mul_f32 v[10:11], v[12:13], v[10:11]
	v_mov_b32_e32 v6, v3
	v_add_f32_e32 v2, v10, v11
	v_mul_f32_e32 v12, 0x3e38aa3b, v2
	v_and_b32_e32 v2, 0xffff0000, v24
	v_and_b32_e32 v10, 0xffff0000, v20
	v_cndmask_b32_e64 v11, v2, -v2, vcc
	v_pk_mul_f32 v[2:3], v[6:7], v[10:11]
	v_mov_b32_e32 v6, v4
	v_add_f32_e32 v2, v2, v3
	v_mul_f32_e32 v2, 0x3e38aa3b, v2
	v_lshlrev_b32_e32 v3, 16, v25
	v_cvt_pk_bf16_f32 v52, v12, v2
	v_lshlrev_b32_e32 v2, 16, v21
	v_cndmask_b32_e64 v3, v3, -v3, vcc
	v_mov_b32_e32 v7, v8
	v_pk_mul_f32 v[2:3], v[6:7], v[2:3]
	v_mov_b32_e32 v8, v5
	v_add_f32_e32 v2, v2, v3
	v_and_b32_e32 v3, 0xffff0000, v25
	v_mul_f32_e32 v4, 0x3e38aa3b, v2
	v_and_b32_e32 v2, 0xffff0000, v21
	v_cndmask_b32_e64 v3, v3, -v3, vcc
	v_pk_mul_f32 v[2:3], v[8:9], v[2:3]
	s_nop 0
	v_add_f32_e32 v2, v2, v3
	v_mul_f32_e32 v2, 0x3e38aa3b, v2
	v_cvt_pk_bf16_f32 v53, v4, v2
	s_waitcnt vmcnt(2)
	v_mov_b32_e32 v2, v114
	v_mov_b32_e32 v3, v115
	v_mov_b32_e32 v4, v116
	v_mov_b32_e32 v5, v117
	v_lshlrev_b32_e32 v6, 16, v2
	v_and_b32_e32 v7, 0xffff0000, v2
	v_lshlrev_b32_e32 v2, 16, v3
	v_and_b32_e32 v3, 0xffff0000, v3
	v_pk_mul_f32 v[2:3], v[2:3], s[38:39] op_sel_hi:[1,0]
	v_pk_mul_f32 v[6:7], v[6:7], s[38:39] op_sel_hi:[1,0]
	v_cvt_pk_bf16_f32 v55, v2, v3
	v_lshlrev_b32_e32 v2, 16, v4
	v_and_b32_e32 v3, 0xffff0000, v4
	v_pk_mul_f32 v[2:3], v[2:3], s[38:39] op_sel_hi:[1,0]
	v_cvt_pk_bf16_f32 v54, v6, v7
	v_cvt_pk_bf16_f32 v56, v2, v3
	v_lshlrev_b32_e32 v2, 16, v5
	v_and_b32_e32 v3, 0xffff0000, v5
	v_pk_mul_f32 v[2:3], v[2:3], s[38:39] op_sel_hi:[1,0]
	s_nop 0
	v_cvt_pk_bf16_f32 v57, v2, v3
	s_waitcnt vmcnt(1)
; #define LAS __attribute__((address_space(3)))
; __device__ __forceinline__ float bf_lo(unsigned u) { return __uint_as_float(u << 16); }
; template <int MODE> __device__ __forceinline__ void flash_run(const bf16x8* kb, const bf16x8* vb, const bf16x8 (&q)[4], int nsteps, const LAS unsigned* list, int base, int t, int t0, int qi, int hi, float& m, float& l, f32x16 (&O)[2]) {
;     if (nsteps <= 0) return;
;     bf16x8 kA[4], vA[4], kB[4], vB[4], kC[4], vC[4]; int x0A, x0B, x0C, vmA, vmB, vmC; unsigned spA, spB, spC;
;     ...
;     FR_LOAD(0, kA, vA, x0A, spA, vmA); FR_LOAD(1, kB, vB, x0B, spB, vmB);
; __device__ __forceinline__ void nsa_tile(const Ctx& C, int b, int g, int t0) {
;     ...
;         bf16x8 qr[4];
;         {
;             const bf16_t* qp = P + tok * PP + PC_Q + head * 64;
; #pragma unroll
;             for (int s = 1; s < 4; ++s) qr[s] = scale_q(*(const u32x4*)(qp + 16 * s + 8 * hi), QS);
;             const u32x4 mv4 = *(const u32x4*)(qp + 8 * hi), pv4 = *(const u32x4*)(qp + 8 * (hi ^ 1));
;             const float* rt = (const float*)(C.ws + WS_ROPE) + tok * 16;
;             const f32x4 ca = *(const f32x4*)rt, cb2 = *(const f32x4*)(rt + 4), sa = *(const f32x4*)(rt + 8), sb = *(const f32x4*)(rt + 12);
;             const float cs[8] = {ca.x, ca.y, ca.z, ca.w, cb2.x, cb2.y, cb2.z, cb2.w}, sn[8] = {sa.x, sa.y, sa.z, sa.w, sb.x, sb.y, sb.z, sb.w};
;             const float mv[8] = {bf_lo(mv4.x), bf_hi(mv4.x), bf_lo(mv4.y), bf_hi(mv4.y), bf_lo(mv4.z), bf_hi(mv4.z), bf_lo(mv4.w), bf_hi(mv4.w)};
;             const float pp[8] = {bf_lo(pv4.x), bf_hi(pv4.x), bf_lo(pv4.y), bf_hi(pv4.y), bf_lo(pv4.z), bf_hi(pv4.z), bf_lo(pv4.w), bf_hi(pv4.w)};
;             const float sg = hi ? 1.f : -1.f; float o[8];
; #pragma unroll
;             for (int e = 0; e < 8; ++e) o[e] = (mv[e] * cs[e] + sg * pp[e] * sn[e]) * QS;
;             qr[0] = pack_p(o);
;         }
;         const bf16x8* kb = (const bf16x8*)(C.ws + WS_KWIN) + (size_t)bg * 512 * 4 * 64 + lane;
;         const bf16x8* vb = (const bf16x8*)(C.ws + WS_VWIN) + (size_t)bg * 1024 * 2 * 64 + lane;
;         float m = -1e30f, l = 0.f; f32x16 O[2];
; #pragma unroll
;         for (int i = 0; i < 16; ++i) { O[0][i] = 0.f; O[1][i] = 0.f; }
;         const int tlo = (t0 - 511 > 0 ? t0 - 511 : 0) >> 5, thi = (t0 + 7) >> 5;
;         flash_run<1>(kb, vb, qr, thi - tlo + 1, (const LAS unsigned*)imp, tlo, t, t0, qi, hi, m, l, O);
	v_mov_b32_e32 v2, v118
	v_mov_b32_e32 v3, v119
	v_mov_b32_e32 v4, v120
	v_mov_b32_e32 v5, v121
	v_lshlrev_b32_e32 v6, 16, v2
	v_and_b32_e32 v7, 0xffff0000, v2
	v_lshlrev_b32_e32 v2, 16, v3
	v_and_b32_e32 v3, 0xffff0000, v3
	v_pk_mul_f32 v[2:3], v[2:3], s[38:39] op_sel_hi:[1,0]
	v_pk_mul_f32 v[6:7], v[6:7], s[38:39] op_sel_hi:[1,0]
	v_cvt_pk_bf16_f32 v59, v2, v3
	v_lshlrev_b32_e32 v2, 16, v4
	v_and_b32_e32 v3, 0xffff0000, v4
	v_pk_mul_f32 v[2:3], v[2:3], s[38:39] op_sel_hi:[1,0]
	v_cvt_pk_bf16_f32 v58, v6, v7
	v_cvt_pk_bf16_f32 v60, v2, v3
	v_lshlrev_b32_e32 v2, 16, v5
	v_and_b32_e32 v3, 0xffff0000, v5
	v_pk_mul_f32 v[2:3], v[2:3], s[38:39] op_sel_hi:[1,0]
	s_nop 0
	v_cvt_pk_bf16_f32 v61, v2, v3
	s_waitcnt vmcnt(0)
	v_mov_b32_e32 v2, v122
	v_mov_b32_e32 v3, v123
	v_mov_b32_e32 v4, v124
	v_mov_b32_e32 v5, v125
	v_lshlrev_b32_e32 v6, 16, v2
	v_and_b32_e32 v7, 0xffff0000, v2
	v_lshlrev_b32_e32 v2, 16, v3
	v_and_b32_e32 v3, 0xffff0000, v3
	v_pk_mul_f32 v[2:3], v[2:3], s[38:39] op_sel_hi:[1,0]
	v_pk_mul_f32 v[6:7], v[6:7], s[38:39] op_sel_hi:[1,0]
	v_cvt_pk_bf16_f32 v63, v2, v3
	v_lshlrev_b32_e32 v2, 16, v4
	v_and_b32_e32 v3, 0xffff0000, v4
	v_pk_mul_f32 v[2:3], v[2:3], s[38:39] op_sel_hi:[1,0]
	v_cvt_pk_bf16_f32 v62, v6, v7
	v_cvt_pk_bf16_f32 v64, v2, v3
	v_lshlrev_b32_e32 v2, 16, v5
	v_and_b32_e32 v3, 0xffff0000, v5
	v_pk_mul_f32 v[2:3], v[2:3], s[38:39] op_sel_hi:[1,0]
	v_lshl_add_u64 v[4:5], v[164:165], 0, s[10:11]
	v_cvt_pk_bf16_f32 v65, v2, v3
	v_lshl_add_u64 v[2:3], v[162:163], 0, s[10:11]
	global_load_dwordx4 v[94:97], v[2:3], off
	global_load_dwordx4 v[90:93], v[2:3], off offset:1024
	global_load_dwordx4 v[82:85], v[2:3], off offset:2048
	global_load_dwordx4 v[86:89], v[2:3], off offset:3072
	global_load_dwordx4 v[74:77], v[4:5], off
	global_load_dwordx4 v[70:73], v[4:5], off offset:1024
	global_load_dwordx4 v[66:69], v[4:5], off offset:2048
	global_load_dwordx4 v[78:81], v[4:5], off offset:3072
	s_cmp_lg_u32 s4, s0
	s_cselect_b64 s[10:11], -1, 0
	s_cmp_lg_u64 s[10:11], 0
	s_addc_u32 s6, s0, 0
	s_lshl_b32 s10, s6, 5
	s_or_b32 s1, s10, 31
	s_cmp_gt_u32 s1, s97
	s_cselect_b64 s[12:13], -1, 0
	s_cmp_lt_i32 s10, s16
	s_cselect_b64 s[18:19], -1, 0
	s_or_b64 s[12:13], s[12:13], s[18:19]
	s_and_b64 s[12:13], s[12:13], exec
	s_cselect_b32 s11, 2, 0
	s_lshl_b64 s[12:13], s[6:7], 12
	v_lshl_add_u64 v[2:3], v[162:163], 0, s[12:13]
	v_lshl_add_u64 v[4:5], v[164:165], 0, s[12:13]
	global_load_dwordx4 v[114:117], v[2:3], off
	global_load_dwordx4 v[118:121], v[2:3], off offset:1024
	global_load_dwordx4 v[122:125], v[2:3], off offset:2048
	global_load_dwordx4 v[126:129], v[2:3], off offset:3072
	global_load_dwordx4 v[98:101], v[4:5], off
	global_load_dwordx4 v[102:105], v[4:5], off offset:1024
	global_load_dwordx4 v[106:109], v[4:5], off offset:2048
	global_load_dwordx4 v[110:113], v[4:5], off offset:3072
	v_mov_b32_e32 v16, v1
	v_mov_b32_e32 v17, v1
	v_mov_b32_e32 v2, v1
	v_mov_b32_e32 v3, v1
	v_mov_b32_e32 v4, v1
	v_mov_b32_e32 v5, v1
	v_mov_b32_e32 v6, v1
	v_mov_b32_e32 v7, v1
	v_mov_b32_e32 v8, v1
	v_mov_b32_e32 v9, v1
	v_mov_b32_e32 v10, v1
	v_mov_b32_e32 v11, v1
	v_mov_b32_e32 v12, v1
	v_mov_b32_e32 v13, v1
	v_mov_b32_e32 v14, v1
	v_mov_b32_e32 v15, v1
	v_mov_b64_e32 v[32:33], v[16:17]
	v_add_u32_e32 v167, 0x1ff, v218
	v_mov_b32_e32 v166, 0
	v_mov_b32_e32 v168, 0xf149f2ca
	v_mov_b64_e32 v[30:31], v[14:15]
	v_mov_b64_e32 v[28:29], v[12:13]
	v_mov_b64_e32 v[26:27], v[10:11]
	v_mov_b64_e32 v[24:25], v[8:9]
	v_mov_b64_e32 v[22:23], v[6:7]
	v_mov_b64_e32 v[20:21], v[4:5]
	v_mov_b64_e32 v[18:19], v[2:3]
	v_mov_b64_e32 v[214:215], v[216:217]
	v_mov_b64_e32 v[236:237], 0x1ff
	s_branch .LBB0_869
